# P0: weight f32 loads marked nt (read-once stream); x->bf16 loop de-serialized
# baseline (speedup 1.0000x reference)
.LBB0_20:
	s_mul_hi_i32 s18, s95, 0x54c807f3
	s_lshr_b32 s19, s18, 31
	s_ashr_i32 s18, s18, 13
	s_add_i32 s42, s18, s19
	s_mul_i32 s18, s42, 0xffff9f60
	s_add_i32 s96, s95, s18
	s_cmpk_gt_i32 s96, 0x2bff
	s_mov_b64 s[18:19], -1
	s_cbranch_scc0 .LBB0_194
	s_cmpk_gt_u32 s96, 0x41ff
	s_cbranch_scc0 .LBB0_191
	s_ashr_i32 s43, s42, 31
	s_mul_i32 s19, s42, 0x5820000
	s_mul_hi_i32 s18, s42, 0x5820000
	s_add_u32 s50, s33, s19
	s_addc_u32 s51, s35, s18
	s_mul_i32 s18, s42, 3
	s_ashr_i32 s19, s18, 31
	s_lshl_b64 s[18:19], s[18:19], 13
	s_add_u32 s46, s30, s18
	s_addc_u32 s47, s31, s19
	s_add_u32 s48, s62, s18
	s_addc_u32 s49, s63, s19
	s_mul_i32 s19, s42, 0x16800
	s_mul_hi_i32 s18, s42, 0x16800
	s_add_u32 s44, s64, s19
	s_addc_u32 s45, s65, s18
	s_cmpk_gt_u32 s96, 0x47ff
	s_mov_b64 s[18:19], -1
	s_cbranch_scc0 .LBB0_152
	s_cmpk_gt_u32 s96, 0x481f
	s_cbranch_scc0 .LBB0_113
	s_cmpk_gt_u32 s96, 0x4c1f
	s_cbranch_scc0 .LBB0_74
	s_cmpk_gt_u32 s96, 0x581f
	s_cbranch_scc0 .LBB0_35
	s_cmpk_gt_u32 s96, 0x589f
	s_cbranch_scc0 .LBB0_32
	s_bfe_u32 s66, s96, 0x10002
	s_and_b32 s97, s96, 3
	s_lshl_b64 s[52:53], s[42:43], 24
	s_lshl_b64 s[18:19], s[42:43], 23
	s_cmpk_gt_u32 s96, 0x5c9f
	s_mov_b64 s[54:55], -1
	s_cbranch_scc0 .LBB0_29
	s_add_i32 s40, s96, 0xffffa360
	s_lshr_b32 s54, s40, 5
	s_lshr_b32 s40, s40, 1
	s_and_b32 s54, s54, 0x3fffffe
	s_and_b32 s40, s40, 28
	s_or_b32 s54, s54, s66
	s_or_b32 s55, s40, s97
	s_add_u32 vcc_lo, s60, s52
	s_addc_u32 vcc_hi, s61, s53
	s_lshl_b32 s40, s54, 6
	s_lshl_b32 s54, s55, 6
	s_add_u32 s90, s67, s18
	s_mov_b32 s91, s70
	s_addc_u32 s70, s68, s19
	s_lshl_b32 s55, s55, 8
	v_or_b32_e32 v130, s40, v1
	s_add_u32 vcc_lo, vcc_lo, s55
	s_addc_u32 vcc_hi, vcc_hi, 0
	v_mov_b32_e32 v33, v25
	v_mov_b32_e32 v131, v25
	v_or_b32_e32 v4, 4, v130
	v_mov_b32_e32 v5, v25
	s_waitcnt vmcnt(9)
	v_or_b32_e32 v10, 8, v130
	v_mov_b32_e32 v11, v25
	v_or_b32_e32 v12, 12, v130
	v_mov_b32_e32 v13, v25
	v_or_b32_e32 v18, 16, v130
	v_mov_b32_e32 v19, v25
	v_or_b32_e32 v20, 20, v130
	v_mov_b32_e32 v21, v25
	s_waitcnt lgkmcnt(3)
	v_or_b32_e32 v38, 24, v130
	v_mov_b32_e32 v39, v25
	s_waitcnt lgkmcnt(2)
	v_or_b32_e32 v40, 28, v130
	v_mov_b32_e32 v41, v25
	s_waitcnt lgkmcnt(0)
	v_or_b32_e32 v46, 32, v130
	v_mov_b32_e32 v47, v25
	v_or_b32_e32 v48, 36, v130
	v_mov_b32_e32 v49, v25
	v_or_b32_e32 v110, 40, v130
	v_mov_b32_e32 v111, v25
	v_or_b32_e32 v112, 44, v130
	v_mov_b32_e32 v113, v25
	v_or_b32_e32 v118, 48, v130
	v_mov_b32_e32 v119, v25
	v_or_b32_e32 v120, 52, v130
	v_mov_b32_e32 v121, v25
	v_lshl_add_u64 v[132:133], vcc, 0, v[32:33]
	v_lshlrev_b64 v[2:3], 13, v[130:131]
	v_lshlrev_b64 v[4:5], 13, v[4:5]
	v_lshlrev_b64 v[10:11], 13, v[10:11]
	v_lshlrev_b64 v[12:13], 13, v[12:13]
	v_lshlrev_b64 v[18:19], 13, v[18:19]
	v_lshlrev_b64 v[20:21], 13, v[20:21]
	v_lshlrev_b64 v[38:39], 13, v[38:39]
	v_lshlrev_b64 v[40:41], 13, v[40:41]
	v_lshlrev_b64 v[46:47], 13, v[46:47]
	v_lshlrev_b64 v[48:49], 13, v[48:49]
	v_lshlrev_b64 v[110:111], 13, v[110:111]
	v_lshlrev_b64 v[112:113], 13, v[112:113]
	v_lshlrev_b64 v[118:119], 13, v[118:119]
	v_lshlrev_b64 v[120:121], 13, v[120:121]
	v_lshl_add_u64 v[2:3], v[132:133], 0, v[2:3]
	s_waitcnt vmcnt(8)
	v_lshl_add_u64 v[6:7], v[132:133], 0, v[4:5]
	v_lshl_add_u64 v[10:11], v[132:133], 0, v[10:11]
	v_lshl_add_u64 v[14:15], v[132:133], 0, v[12:13]
	v_lshl_add_u64 v[18:19], v[132:133], 0, v[18:19]
	v_lshl_add_u64 v[34:35], v[132:133], 0, v[20:21]
	v_lshl_add_u64 v[38:39], v[132:133], 0, v[38:39]
	v_lshl_add_u64 v[42:43], v[132:133], 0, v[40:41]
	v_lshl_add_u64 v[46:47], v[132:133], 0, v[46:47]
	v_lshl_add_u64 v[106:107], v[132:133], 0, v[48:49]
	v_lshl_add_u64 v[110:111], v[132:133], 0, v[110:111]
	v_lshl_add_u64 v[114:115], v[132:133], 0, v[112:113]
	v_lshl_add_u64 v[118:119], v[132:133], 0, v[118:119]
	v_lshl_add_u64 v[122:123], v[132:133], 0, v[120:121]
	global_load_dwordx4 v[2:5], v[2:3], off nt
	s_nop 0
	global_load_dwordx4 v[6:9], v[6:7], off nt
	s_nop 0
	global_load_dwordx4 v[10:13], v[10:11], off nt
	s_nop 0
	global_load_dwordx4 v[14:17], v[14:15], off nt
	s_nop 0
	global_load_dwordx4 v[18:21], v[18:19], off nt
	s_nop 0
	global_load_dwordx4 v[34:37], v[34:35], off nt
	s_nop 0
	global_load_dwordx4 v[38:41], v[38:39], off nt
	s_nop 0
	global_load_dwordx4 v[42:45], v[42:43], off nt
	s_nop 0
	global_load_dwordx4 v[46:49], v[46:47], off nt
	s_nop 0
	global_load_dwordx4 v[106:109], v[106:107], off nt
	s_nop 0
	global_load_dwordx4 v[110:113], v[110:111], off nt
	s_nop 0
	global_load_dwordx4 v[114:117], v[114:115], off nt
	s_nop 0
	global_load_dwordx4 v[118:121], v[118:119], off nt
	s_nop 0
	global_load_dwordx4 v[122:125], v[122:123], off nt
	v_or_b32_e32 v126, 56, v130
	v_mov_b32_e32 v127, v25
	v_lshlrev_b64 v[126:127], 13, v[126:127]
	v_lshl_add_u64 v[126:127], v[132:133], 0, v[126:127]
	v_or_b32_e32 v130, 60, v130
	global_load_dwordx4 v[126:129], v[126:127], off nt
	v_lshlrev_b64 v[130:131], 13, v[130:131]
	v_lshl_add_u64 v[130:131], v[132:133], 0, v[130:131]
	global_load_dwordx4 v[130:133], v[130:131], off nt
	s_lshl_b64 vcc, s[40:41], 1
	s_waitcnt vmcnt(15)
	ds_write2_b32 v23, v2, v3 offset1:1
	ds_write2_b32 v23, v4, v5 offset0:2 offset1:3
	s_waitcnt vmcnt(14)
	ds_write2_b32 v58, v6, v7 offset1:1
	ds_write2_b32 v59, v8, v9 offset1:1
	s_waitcnt vmcnt(13)
	ds_write2_b32 v60, v10, v11 offset1:1
	ds_write2_b32 v61, v12, v13 offset1:1
	s_waitcnt vmcnt(12)
	ds_write2_b32 v62, v14, v15 offset1:1
	ds_write2_b32 v63, v16, v17 offset1:1
	s_waitcnt vmcnt(11)
	ds_write2_b32 v64, v18, v19 offset1:1
	ds_write2_b32 v65, v20, v21 offset1:1
	s_waitcnt vmcnt(10)
	ds_write2_b32 v66, v34, v35 offset1:1
	ds_write2_b32 v67, v36, v37 offset1:1
	s_waitcnt vmcnt(9)
	ds_write2_b32 v68, v38, v39 offset1:1
	ds_write2_b32 v69, v40, v41 offset1:1
	s_waitcnt vmcnt(8)
	ds_write2_b32 v70, v42, v43 offset1:1
	ds_write2_b32 v71, v44, v45 offset1:1
	s_waitcnt vmcnt(7)
	ds_write2_b32 v72, v46, v47 offset1:1
	ds_write2_b32 v73, v48, v49 offset1:1
	s_waitcnt vmcnt(6)
	ds_write2_b32 v74, v106, v107 offset1:1
	ds_write2_b32 v75, v108, v109 offset1:1
	s_waitcnt vmcnt(5)
	ds_write2_b32 v76, v110, v111 offset1:1
	ds_write2_b32 v77, v112, v113 offset1:1
	s_waitcnt vmcnt(4)
	ds_write2_b32 v78, v114, v115 offset1:1
	ds_write2_b32 v79, v116, v117 offset1:1
	s_waitcnt vmcnt(3)
	ds_write2_b32 v80, v118, v119 offset1:1
	ds_write2_b32 v81, v120, v121 offset1:1
	s_waitcnt vmcnt(2)
	ds_write2_b32 v82, v122, v123 offset1:1
	ds_write2_b32 v83, v124, v125 offset1:1
	s_waitcnt vmcnt(1)
	ds_write2_b32 v84, v126, v127 offset1:1
	ds_write2_b32 v85, v128, v129 offset1:1
	s_waitcnt vmcnt(0)
	ds_write2_b32 v86, v130, v131 offset1:1
	ds_write2_b32 v87, v132, v133 offset1:1
	s_waitcnt lgkmcnt(0)
	ds_read2_b32 v[6:7], v29 offset1:8
	ds_read2_b32 v[8:9], v29 offset0:65 offset1:73
	ds_read2_b32 v[10:11], v29 offset0:130 offset1:138
	ds_read2_b32 v[12:13], v29 offset0:195 offset1:203
	ds_read2_b32 v[14:15], v88 offset0:4 offset1:12
	ds_read2_b32 v[16:17], v88 offset0:69 offset1:77
	ds_read2_b32 v[18:19], v88 offset0:134 offset1:142
	ds_read2_b32 v[20:21], v88 offset0:199 offset1:207
	s_add_u32 vcc_lo, s90, vcc_lo
	s_addc_u32 vcc_hi, s70, vcc_hi
	s_waitcnt lgkmcnt(6)
	v_cvt_pk_bf16_f32 v2, v6, v8
	v_or_b32_e32 v6, s54, v27
	v_lshl_add_u64 v[34:35], vcc, 0, v[24:25]
	v_lshlrev_b32_e32 v36, 12, v6
	v_mov_b32_e32 v37, v25
	s_waitcnt lgkmcnt(4)
	v_cvt_pk_bf16_f32 v3, v10, v12
	s_waitcnt lgkmcnt(2)
	v_cvt_pk_bf16_f32 v4, v14, v16
	s_waitcnt lgkmcnt(0)
	v_cvt_pk_bf16_f32 v5, v18, v20
	v_lshl_add_u64 v[36:37], v[34:35], 0, v[36:37]
	global_store_dwordx4 v[36:37], v[2:5], off nt
	v_or_b32_e32 v6, s54, v50
	v_lshlrev_b32_e32 v6, 12, v6
	v_cvt_pk_bf16_f32 v2, v7, v9
	v_cvt_pk_bf16_f32 v3, v11, v13
	v_cvt_pk_bf16_f32 v4, v15, v17
	v_cvt_pk_bf16_f32 v5, v19, v21
	ds_read2_b32 v[8:9], v29 offset0:16 offset1:24
	ds_read2_b32 v[10:11], v29 offset0:81 offset1:89
	ds_read2_b32 v[12:13], v29 offset0:146 offset1:154
	ds_read2_b32 v[14:15], v29 offset0:211 offset1:219
	ds_read2_b32 v[16:17], v88 offset0:20 offset1:28
	ds_read2_b32 v[18:19], v88 offset0:85 offset1:93
	ds_read2_b32 v[20:21], v88 offset0:150 offset1:158
	ds_read2_b32 v[36:37], v88 offset0:215 offset1:223
	v_mov_b32_e32 v7, v25
	v_lshl_add_u64 v[6:7], v[34:35], 0, v[6:7]
	global_store_dwordx4 v[6:7], v[2:5], off nt
	v_or_b32_e32 v6, s54, v51
	v_lshlrev_b32_e32 v6, 12, v6
	v_mov_b32_e32 v7, v25
	s_waitcnt lgkmcnt(6)
	v_cvt_pk_bf16_f32 v2, v8, v10
	s_waitcnt lgkmcnt(4)
	v_cvt_pk_bf16_f32 v3, v12, v14
	s_waitcnt lgkmcnt(2)
	v_cvt_pk_bf16_f32 v4, v16, v18
	s_waitcnt lgkmcnt(0)
	v_cvt_pk_bf16_f32 v5, v20, v36
	v_lshl_add_u64 v[6:7], v[34:35], 0, v[6:7]
	global_store_dwordx4 v[6:7], v[2:5], off nt
	v_or_b32_e32 v6, s54, v52
	v_lshlrev_b32_e32 v6, 12, v6
	v_cvt_pk_bf16_f32 v2, v9, v11
	v_cvt_pk_bf16_f32 v3, v13, v15
	v_cvt_pk_bf16_f32 v4, v17, v19
	v_cvt_pk_bf16_f32 v5, v21, v37
	ds_read2_b32 v[8:9], v29 offset0:32 offset1:40
	ds_read2_b32 v[10:11], v29 offset0:97 offset1:105
	ds_read2_b32 v[12:13], v29 offset0:162 offset1:170
	ds_read2_b32 v[14:15], v29 offset0:227 offset1:235
	ds_read2_b32 v[16:17], v88 offset0:36 offset1:44
	ds_read2_b32 v[18:19], v88 offset0:101 offset1:109
	ds_read2_b32 v[20:21], v88 offset0:166 offset1:174
	ds_read2_b32 v[36:37], v88 offset0:231 offset1:239
	v_mov_b32_e32 v7, v25
	v_lshl_add_u64 v[6:7], v[34:35], 0, v[6:7]
	global_store_dwordx4 v[6:7], v[2:5], off nt
	v_or_b32_e32 v6, s54, v53
	v_lshlrev_b32_e32 v6, 12, v6
	v_mov_b32_e32 v7, v25
	s_waitcnt lgkmcnt(6)
	v_cvt_pk_bf16_f32 v2, v8, v10
	s_waitcnt lgkmcnt(4)
	v_cvt_pk_bf16_f32 v3, v12, v14
	s_waitcnt lgkmcnt(2)
	v_cvt_pk_bf16_f32 v4, v16, v18
	s_waitcnt lgkmcnt(0)
	v_cvt_pk_bf16_f32 v5, v20, v36
	v_lshl_add_u64 v[6:7], v[34:35], 0, v[6:7]
	global_store_dwordx4 v[6:7], v[2:5], off nt
	v_or_b32_e32 v6, s54, v54
	v_lshlrev_b32_e32 v6, 12, v6
	v_cvt_pk_bf16_f32 v2, v9, v11
	v_cvt_pk_bf16_f32 v3, v13, v15
	v_cvt_pk_bf16_f32 v4, v17, v19
	v_cvt_pk_bf16_f32 v5, v21, v37
	ds_read2_b32 v[8:9], v29 offset0:48 offset1:56
	ds_read2_b32 v[10:11], v29 offset0:113 offset1:121
	ds_read2_b32 v[12:13], v29 offset0:178 offset1:186
	ds_read2_b32 v[14:15], v29 offset0:243 offset1:251
	ds_read2_b32 v[16:17], v88 offset0:52 offset1:60
	ds_read2_b32 v[18:19], v88 offset0:117 offset1:125
	ds_read2_b32 v[20:21], v88 offset0:182 offset1:190
	ds_read2_b32 v[36:37], v88 offset0:247 offset1:255
	v_mov_b32_e32 v7, v25
	v_lshl_add_u64 v[6:7], v[34:35], 0, v[6:7]
	global_store_dwordx4 v[6:7], v[2:5], off nt
	v_or_b32_e32 v6, s54, v55
	v_lshlrev_b32_e32 v6, 12, v6
	v_mov_b32_e32 v7, v25
	s_waitcnt lgkmcnt(6)
	v_cvt_pk_bf16_f32 v2, v8, v10
	s_waitcnt lgkmcnt(4)
	v_cvt_pk_bf16_f32 v3, v12, v14
	s_waitcnt lgkmcnt(2)
	v_cvt_pk_bf16_f32 v4, v16, v18
	s_waitcnt lgkmcnt(0)
	v_cvt_pk_bf16_f32 v5, v20, v36
	v_lshl_add_u64 v[6:7], v[34:35], 0, v[6:7]
	global_store_dwordx4 v[6:7], v[2:5], off nt
	v_or_b32_e32 v6, s54, v56
	v_lshlrev_b32_e32 v6, 12, v6
	v_mov_b32_e32 v7, v25
	v_cvt_pk_bf16_f32 v2, v9, v11
	v_cvt_pk_bf16_f32 v3, v13, v15
	v_cvt_pk_bf16_f32 v4, v17, v19
	v_cvt_pk_bf16_f32 v5, v21, v37
	v_lshl_add_u64 v[6:7], v[34:35], 0, v[6:7]
	global_store_dwordx4 v[6:7], v[2:5], off nt
	s_waitcnt lgkmcnt(0)
	s_mov_b32 s90, 0x8000
	s_mov_b32 s70, s91
	s_mov_b32 s91, 0x10000
	s_mov_b64 s[54:55], 0
.LBB0_29:
	s_andn2_b64 vcc, exec, s[54:55]
	s_cbranch_vccnz .LBB0_31
	s_add_i32 s40, s96, 0xffffa760
	s_lshr_b32 s54, s40, 5
	s_lshr_b32 s40, s40, 1
	s_and_b32 s54, s54, 0x3fffffe
	s_and_b32 s40, s40, 28
	s_or_b32 s54, s54, s66
	s_or_b32 s55, s40, s97
	s_add_u32 s66, s58, s52
	s_addc_u32 s53, s59, s53
	s_lshl_b32 s40, s54, 6
	s_lshl_b32 s52, s55, 6
	s_add_u32 s54, s69, s18
	s_addc_u32 s97, s70, s19
	s_lshl_b32 s18, s55, 8
	v_or_b32_e32 v130, s40, v1
	s_add_u32 s18, s66, s18
	s_addc_u32 s19, s53, 0
	v_mov_b32_e32 v33, v25
	v_mov_b32_e32 v131, v25
	v_or_b32_e32 v4, 4, v130
	v_mov_b32_e32 v5, v25
	s_waitcnt vmcnt(9)
	v_or_b32_e32 v10, 8, v130
	v_mov_b32_e32 v11, v25
	v_or_b32_e32 v12, 12, v130
	v_mov_b32_e32 v13, v25
	v_or_b32_e32 v18, 16, v130
	v_mov_b32_e32 v19, v25
	v_or_b32_e32 v20, 20, v130
	v_mov_b32_e32 v21, v25
	s_waitcnt lgkmcnt(3)
	v_or_b32_e32 v38, 24, v130
	v_mov_b32_e32 v39, v25
	s_waitcnt lgkmcnt(2)
	v_or_b32_e32 v40, 28, v130
	v_mov_b32_e32 v41, v25
	s_waitcnt lgkmcnt(0)
	v_or_b32_e32 v46, 32, v130
	v_mov_b32_e32 v47, v25
	v_or_b32_e32 v48, 36, v130
	v_mov_b32_e32 v49, v25
	v_or_b32_e32 v110, 40, v130
	v_mov_b32_e32 v111, v25
	v_or_b32_e32 v112, 44, v130
	v_mov_b32_e32 v113, v25
	v_or_b32_e32 v118, 48, v130
	v_mov_b32_e32 v119, v25
	v_or_b32_e32 v120, 52, v130
	v_mov_b32_e32 v121, v25
	v_lshl_add_u64 v[132:133], s[18:19], 0, v[32:33]
	v_lshlrev_b64 v[2:3], 13, v[130:131]
	v_lshlrev_b64 v[4:5], 13, v[4:5]
	v_lshlrev_b64 v[10:11], 13, v[10:11]
	v_lshlrev_b64 v[12:13], 13, v[12:13]
	v_lshlrev_b64 v[18:19], 13, v[18:19]
	v_lshlrev_b64 v[20:21], 13, v[20:21]
	v_lshlrev_b64 v[38:39], 13, v[38:39]
	v_lshlrev_b64 v[40:41], 13, v[40:41]
	v_lshlrev_b64 v[46:47], 13, v[46:47]
	v_lshlrev_b64 v[48:49], 13, v[48:49]
	v_lshlrev_b64 v[110:111], 13, v[110:111]
	v_lshlrev_b64 v[112:113], 13, v[112:113]
	v_lshlrev_b64 v[118:119], 13, v[118:119]
	v_lshlrev_b64 v[120:121], 13, v[120:121]
	v_lshl_add_u64 v[2:3], v[132:133], 0, v[2:3]
	s_waitcnt vmcnt(8)
	v_lshl_add_u64 v[6:7], v[132:133], 0, v[4:5]
	v_lshl_add_u64 v[10:11], v[132:133], 0, v[10:11]
	v_lshl_add_u64 v[14:15], v[132:133], 0, v[12:13]
	v_lshl_add_u64 v[18:19], v[132:133], 0, v[18:19]
	v_lshl_add_u64 v[34:35], v[132:133], 0, v[20:21]
	v_lshl_add_u64 v[38:39], v[132:133], 0, v[38:39]
	v_lshl_add_u64 v[42:43], v[132:133], 0, v[40:41]
	v_lshl_add_u64 v[46:47], v[132:133], 0, v[46:47]
	v_lshl_add_u64 v[106:107], v[132:133], 0, v[48:49]
	v_lshl_add_u64 v[110:111], v[132:133], 0, v[110:111]
	v_lshl_add_u64 v[114:115], v[132:133], 0, v[112:113]
	v_lshl_add_u64 v[118:119], v[132:133], 0, v[118:119]
	v_lshl_add_u64 v[122:123], v[132:133], 0, v[120:121]
	global_load_dwordx4 v[2:5], v[2:3], off nt
	s_nop 0
	global_load_dwordx4 v[6:9], v[6:7], off nt
	s_nop 0
	global_load_dwordx4 v[10:13], v[10:11], off nt
	s_nop 0
	global_load_dwordx4 v[14:17], v[14:15], off nt
	s_nop 0
	global_load_dwordx4 v[18:21], v[18:19], off nt
	s_nop 0
	global_load_dwordx4 v[34:37], v[34:35], off nt
	s_nop 0
	global_load_dwordx4 v[38:41], v[38:39], off nt
	s_nop 0
	global_load_dwordx4 v[42:45], v[42:43], off nt
	s_nop 0
	global_load_dwordx4 v[46:49], v[46:47], off nt
	s_nop 0
	global_load_dwordx4 v[106:109], v[106:107], off nt
	s_nop 0
	global_load_dwordx4 v[110:113], v[110:111], off nt
	s_nop 0
	global_load_dwordx4 v[114:117], v[114:115], off nt
	s_nop 0
	global_load_dwordx4 v[118:121], v[118:119], off nt
	s_nop 0
	global_load_dwordx4 v[122:125], v[122:123], off nt
	v_or_b32_e32 v126, 56, v130
	v_mov_b32_e32 v127, v25
	v_lshlrev_b64 v[126:127], 13, v[126:127]
	v_lshl_add_u64 v[126:127], v[132:133], 0, v[126:127]
	v_or_b32_e32 v130, 60, v130
	global_load_dwordx4 v[126:129], v[126:127], off nt
	v_lshlrev_b64 v[130:131], 13, v[130:131]
	v_lshl_add_u64 v[130:131], v[132:133], 0, v[130:131]
	global_load_dwordx4 v[130:133], v[130:131], off nt
	s_lshl_b64 s[18:19], s[40:41], 1
	s_add_u32 s18, s54, s18
	s_waitcnt vmcnt(15)
	ds_write2_b32 v23, v2, v3 offset1:1
	ds_write2_b32 v23, v4, v5 offset0:2 offset1:3
	s_waitcnt vmcnt(14)
	ds_write2_b32 v58, v6, v7 offset1:1
	ds_write2_b32 v59, v8, v9 offset1:1
	s_waitcnt vmcnt(13)
	ds_write2_b32 v60, v10, v11 offset1:1
	ds_write2_b32 v61, v12, v13 offset1:1
	s_waitcnt vmcnt(12)
	ds_write2_b32 v62, v14, v15 offset1:1
	ds_write2_b32 v63, v16, v17 offset1:1
	s_waitcnt vmcnt(11)
	ds_write2_b32 v64, v18, v19 offset1:1
	ds_write2_b32 v65, v20, v21 offset1:1
	s_waitcnt vmcnt(10)
	ds_write2_b32 v66, v34, v35 offset1:1
	ds_write2_b32 v67, v36, v37 offset1:1
	s_waitcnt vmcnt(9)
	ds_write2_b32 v68, v38, v39 offset1:1
	ds_write2_b32 v69, v40, v41 offset1:1
	s_waitcnt vmcnt(8)
	ds_write2_b32 v70, v42, v43 offset1:1
	ds_write2_b32 v71, v44, v45 offset1:1
	s_waitcnt vmcnt(7)
	ds_write2_b32 v72, v46, v47 offset1:1
	ds_write2_b32 v73, v48, v49 offset1:1
	s_waitcnt vmcnt(6)
	ds_write2_b32 v74, v106, v107 offset1:1
	ds_write2_b32 v75, v108, v109 offset1:1
	s_waitcnt vmcnt(5)
	ds_write2_b32 v76, v110, v111 offset1:1
	ds_write2_b32 v77, v112, v113 offset1:1
	s_waitcnt vmcnt(4)
	ds_write2_b32 v78, v114, v115 offset1:1
	ds_write2_b32 v79, v116, v117 offset1:1
	s_waitcnt vmcnt(3)
	ds_write2_b32 v80, v118, v119 offset1:1
	ds_write2_b32 v81, v120, v121 offset1:1
	s_waitcnt vmcnt(2)
	ds_write2_b32 v82, v122, v123 offset1:1
	ds_write2_b32 v83, v124, v125 offset1:1
	s_waitcnt vmcnt(1)
	ds_write2_b32 v84, v126, v127 offset1:1
	ds_write2_b32 v85, v128, v129 offset1:1
	s_waitcnt vmcnt(0)
	ds_write2_b32 v86, v130, v131 offset1:1
	ds_write2_b32 v87, v132, v133 offset1:1
	s_waitcnt lgkmcnt(0)
	ds_read2_b32 v[6:7], v29 offset1:8
	ds_read2_b32 v[8:9], v29 offset0:65 offset1:73
	ds_read2_b32 v[10:11], v29 offset0:130 offset1:138
	ds_read2_b32 v[12:13], v29 offset0:195 offset1:203
	ds_read2_b32 v[14:15], v88 offset0:4 offset1:12
	ds_read2_b32 v[16:17], v88 offset0:69 offset1:77
	ds_read2_b32 v[18:19], v88 offset0:134 offset1:142
	ds_read2_b32 v[20:21], v88 offset0:199 offset1:207
	s_addc_u32 s19, s97, s19
	s_waitcnt lgkmcnt(6)
	v_cvt_pk_bf16_f32 v2, v6, v8
	v_or_b32_e32 v6, s52, v27
	v_lshl_add_u64 v[34:35], s[18:19], 0, v[24:25]
	v_lshlrev_b32_e32 v36, 12, v6
	v_mov_b32_e32 v37, v25
	s_waitcnt lgkmcnt(4)
	v_cvt_pk_bf16_f32 v3, v10, v12
	s_waitcnt lgkmcnt(2)
	v_cvt_pk_bf16_f32 v4, v14, v16
	s_waitcnt lgkmcnt(0)
	v_cvt_pk_bf16_f32 v5, v18, v20
	v_lshl_add_u64 v[36:37], v[34:35], 0, v[36:37]
	global_store_dwordx4 v[36:37], v[2:5], off nt
	v_or_b32_e32 v6, s52, v50
	v_lshlrev_b32_e32 v6, 12, v6
	v_cvt_pk_bf16_f32 v2, v7, v9
	v_cvt_pk_bf16_f32 v3, v11, v13
	v_cvt_pk_bf16_f32 v4, v15, v17
	v_cvt_pk_bf16_f32 v5, v19, v21
	ds_read2_b32 v[8:9], v29 offset0:16 offset1:24
	ds_read2_b32 v[10:11], v29 offset0:81 offset1:89
	ds_read2_b32 v[12:13], v29 offset0:146 offset1:154
	ds_read2_b32 v[14:15], v29 offset0:211 offset1:219
	ds_read2_b32 v[16:17], v88 offset0:20 offset1:28
	ds_read2_b32 v[18:19], v88 offset0:85 offset1:93
	ds_read2_b32 v[20:21], v88 offset0:150 offset1:158
	ds_read2_b32 v[36:37], v88 offset0:215 offset1:223
	v_mov_b32_e32 v7, v25
	v_lshl_add_u64 v[6:7], v[34:35], 0, v[6:7]
	global_store_dwordx4 v[6:7], v[2:5], off nt
	v_or_b32_e32 v6, s52, v51
	v_lshlrev_b32_e32 v6, 12, v6
	v_mov_b32_e32 v7, v25
	s_waitcnt lgkmcnt(6)
	v_cvt_pk_bf16_f32 v2, v8, v10
	s_waitcnt lgkmcnt(4)
	v_cvt_pk_bf16_f32 v3, v12, v14
	s_waitcnt lgkmcnt(2)
	v_cvt_pk_bf16_f32 v4, v16, v18
	s_waitcnt lgkmcnt(0)
	v_cvt_pk_bf16_f32 v5, v20, v36
	v_lshl_add_u64 v[6:7], v[34:35], 0, v[6:7]
	global_store_dwordx4 v[6:7], v[2:5], off nt
	v_or_b32_e32 v6, s52, v52
	v_lshlrev_b32_e32 v6, 12, v6
	v_cvt_pk_bf16_f32 v2, v9, v11
	v_cvt_pk_bf16_f32 v3, v13, v15
	v_cvt_pk_bf16_f32 v4, v17, v19
	v_cvt_pk_bf16_f32 v5, v21, v37
	ds_read2_b32 v[8:9], v29 offset0:32 offset1:40
	ds_read2_b32 v[10:11], v29 offset0:97 offset1:105
	ds_read2_b32 v[12:13], v29 offset0:162 offset1:170
	ds_read2_b32 v[14:15], v29 offset0:227 offset1:235
	ds_read2_b32 v[16:17], v88 offset0:36 offset1:44
	ds_read2_b32 v[18:19], v88 offset0:101 offset1:109
	ds_read2_b32 v[20:21], v88 offset0:166 offset1:174
	ds_read2_b32 v[36:37], v88 offset0:231 offset1:239
	v_mov_b32_e32 v7, v25
	v_lshl_add_u64 v[6:7], v[34:35], 0, v[6:7]
	global_store_dwordx4 v[6:7], v[2:5], off nt
	v_or_b32_e32 v6, s52, v53
	v_lshlrev_b32_e32 v6, 12, v6
	v_mov_b32_e32 v7, v25
	s_waitcnt lgkmcnt(6)
	v_cvt_pk_bf16_f32 v2, v8, v10
	s_waitcnt lgkmcnt(4)
	v_cvt_pk_bf16_f32 v3, v12, v14
	s_waitcnt lgkmcnt(2)
	v_cvt_pk_bf16_f32 v4, v16, v18
	s_waitcnt lgkmcnt(0)
	v_cvt_pk_bf16_f32 v5, v20, v36
	v_lshl_add_u64 v[6:7], v[34:35], 0, v[6:7]
	global_store_dwordx4 v[6:7], v[2:5], off nt
	v_or_b32_e32 v6, s52, v54
	v_lshlrev_b32_e32 v6, 12, v6
	v_cvt_pk_bf16_f32 v2, v9, v11
	v_cvt_pk_bf16_f32 v3, v13, v15
	v_cvt_pk_bf16_f32 v4, v17, v19
	v_cvt_pk_bf16_f32 v5, v21, v37
	ds_read2_b32 v[8:9], v29 offset0:48 offset1:56
	ds_read2_b32 v[10:11], v29 offset0:113 offset1:121
	ds_read2_b32 v[12:13], v29 offset0:178 offset1:186
	ds_read2_b32 v[14:15], v29 offset0:243 offset1:251
	ds_read2_b32 v[16:17], v88 offset0:52 offset1:60
	ds_read2_b32 v[18:19], v88 offset0:117 offset1:125
	ds_read2_b32 v[20:21], v88 offset0:182 offset1:190
	ds_read2_b32 v[36:37], v88 offset0:247 offset1:255
	v_mov_b32_e32 v7, v25
	v_lshl_add_u64 v[6:7], v[34:35], 0, v[6:7]
	global_store_dwordx4 v[6:7], v[2:5], off nt
	v_or_b32_e32 v6, s52, v55
	v_lshlrev_b32_e32 v6, 12, v6
	v_mov_b32_e32 v7, v25
	s_waitcnt lgkmcnt(6)
	v_cvt_pk_bf16_f32 v2, v8, v10
	s_waitcnt lgkmcnt(4)
	v_cvt_pk_bf16_f32 v3, v12, v14
	s_waitcnt lgkmcnt(2)
	v_cvt_pk_bf16_f32 v4, v16, v18
	s_waitcnt lgkmcnt(0)
	v_cvt_pk_bf16_f32 v5, v20, v36
	v_lshl_add_u64 v[6:7], v[34:35], 0, v[6:7]
	global_store_dwordx4 v[6:7], v[2:5], off nt
	v_or_b32_e32 v6, s52, v56
	v_lshlrev_b32_e32 v6, 12, v6
	v_mov_b32_e32 v7, v25
	v_cvt_pk_bf16_f32 v2, v9, v11
	v_cvt_pk_bf16_f32 v3, v13, v15
	v_cvt_pk_bf16_f32 v4, v17, v19
	v_cvt_pk_bf16_f32 v5, v21, v37
	v_lshl_add_u64 v[6:7], v[34:35], 0, v[6:7]
	global_store_dwordx4 v[6:7], v[2:5], off nt
	s_waitcnt lgkmcnt(0)

.LBB0_32:
	s_andn2_b64 vcc, exec, s[18:19]
	s_cbranch_vccnz .LBB0_34
	s_add_i32 s18, s96, 0xffffa7e0
	s_lshr_b32 s40, s18, 5
	s_lshl_b32 s18, s42, 2
	s_add_i32 s18, s40, s18
	s_ashr_i32 s19, s18, 31
	s_lshl_b64 s[18:19], s[18:19], 19
	s_add_u32 s52, s56, s18
	s_addc_u32 s53, s57, s19
	s_and_b32 s54, s87, 0xc0
	s_and_b32 s55, s84, 0x1c0
	s_lshl_b64 s[18:19], s[42:43], 20
	s_add_u32 s66, s71, s18
	s_addc_u32 s19, s72, s19
	s_lshl_b32 s18, s40, 9
	s_or_b32 s18, s18, s55
	s_lshl_b32 s40, s55, 2
	s_add_u32 s52, s52, s40
	v_or_b32_e32 v4, s54, v1
	s_addc_u32 s53, s53, 0
	v_mov_b32_e32 v33, v25
	v_lshl_add_u64 v[2:3], s[52:53], 0, v[32:33]
	v_lshlrev_b32_e32 v4, 11, v4
	v_mov_b32_e32 v5, v25
	v_lshl_add_u64 v[130:131], v[2:3], 0, v[4:5]
	s_movk_i32 s40, 0x2000
	s_waitcnt vmcnt(8)
	v_add_co_u32_e32 v6, vcc, s40, v130
	s_movk_i32 s40, 0x4000
	s_nop 0
	v_addc_co_u32_e32 v7, vcc, 0, v131, vcc
	v_add_co_u32_e32 v10, vcc, s40, v130
	s_movk_i32 s40, 0x6000
	s_nop 0
	v_addc_co_u32_e32 v11, vcc, 0, v131, vcc
	v_add_co_u32_e32 v14, vcc, s40, v130
	s_mov_b32 s40, 0xa000
	s_nop 0
	v_addc_co_u32_e32 v15, vcc, 0, v131, vcc
	v_add_co_u32_e32 v18, vcc, s90, v130
	global_load_dwordx4 v[2:5], v[130:131], off nt
	s_nop 0
	global_load_dwordx4 v[6:9], v[6:7], off nt
	v_addc_co_u32_e32 v19, vcc, 0, v131, vcc
	v_add_co_u32_e32 v34, vcc, s40, v130
	s_mov_b32 s40, 0xc000
	s_nop 0
	v_addc_co_u32_e32 v35, vcc, 0, v131, vcc
	s_waitcnt lgkmcnt(3)
	v_add_co_u32_e32 v38, vcc, s40, v130
	s_mov_b32 s40, 0xe000
	s_nop 0
	v_addc_co_u32_e32 v39, vcc, 0, v131, vcc
	s_waitcnt lgkmcnt(1)
	v_add_co_u32_e32 v42, vcc, s40, v130
	s_mov_b32 s40, 0x12000
	s_nop 0
	v_addc_co_u32_e32 v43, vcc, 0, v131, vcc
	s_waitcnt lgkmcnt(0)
	v_add_co_u32_e32 v46, vcc, s91, v130
	global_load_dwordx4 v[10:13], v[10:11], off nt
	s_nop 0
	global_load_dwordx4 v[14:17], v[14:15], off nt
	v_addc_co_u32_e32 v47, vcc, 0, v131, vcc
	v_add_co_u32_e32 v106, vcc, s40, v130
	s_mov_b32 s40, 0x14000
	s_nop 0
	v_addc_co_u32_e32 v107, vcc, 0, v131, vcc
	v_add_co_u32_e32 v110, vcc, s40, v130
	s_mov_b32 s40, 0x16000
	s_nop 0
	v_addc_co_u32_e32 v111, vcc, 0, v131, vcc
	v_add_co_u32_e32 v114, vcc, s40, v130
	s_mov_b32 s40, 0x1a000
	s_nop 0
	v_addc_co_u32_e32 v115, vcc, 0, v131, vcc
	v_add_co_u32_e32 v118, vcc, s97, v130
	global_load_dwordx4 v[18:21], v[18:19], off nt
	s_nop 0
	global_load_dwordx4 v[34:37], v[34:35], off nt
	v_addc_co_u32_e32 v119, vcc, 0, v131, vcc
	v_add_co_u32_e32 v122, vcc, s40, v130
	global_load_dwordx4 v[38:41], v[38:39], off nt
	s_nop 0
	global_load_dwordx4 v[42:45], v[42:43], off nt
	v_addc_co_u32_e32 v123, vcc, 0, v131, vcc
	global_load_dwordx4 v[46:49], v[46:47], off nt
	s_nop 0
	global_load_dwordx4 v[106:109], v[106:107], off nt
	s_nop 0
	global_load_dwordx4 v[110:113], v[110:111], off nt
	s_nop 0
	global_load_dwordx4 v[114:117], v[114:115], off nt
	s_nop 0
	global_load_dwordx4 v[118:121], v[118:119], off nt
	s_nop 0
	global_load_dwordx4 v[122:125], v[122:123], off nt
	s_mov_b32 s40, 0x1c000
	v_add_co_u32_e32 v126, vcc, s40, v130
	s_mov_b32 s40, 0x1e000
	s_nop 0
	v_addc_co_u32_e32 v127, vcc, 0, v131, vcc
	global_load_dwordx4 v[126:129], v[126:127], off nt
	v_add_co_u32_e32 v130, vcc, s40, v130
	s_lshl_b32 s40, s54, 1
	s_nop 0
	v_addc_co_u32_e32 v131, vcc, 0, v131, vcc
	global_load_dwordx4 v[130:133], v[130:131], off nt
	s_add_u32 s52, s66, s40
	s_addc_u32 s53, s19, 0
	s_waitcnt vmcnt(15)
	ds_write2_b32 v23, v2, v3 offset1:1
	ds_write2_b32 v23, v4, v5 offset0:2 offset1:3
	s_waitcnt vmcnt(14)
	ds_write2_b32 v58, v6, v7 offset1:1
	ds_write2_b32 v59, v8, v9 offset1:1
	s_waitcnt vmcnt(13)
	ds_write2_b32 v60, v10, v11 offset1:1
	ds_write2_b32 v61, v12, v13 offset1:1
	s_waitcnt vmcnt(12)
	ds_write2_b32 v62, v14, v15 offset1:1
	ds_write2_b32 v63, v16, v17 offset1:1
	s_waitcnt vmcnt(11)
	ds_write2_b32 v64, v18, v19 offset1:1
	ds_write2_b32 v65, v20, v21 offset1:1
	s_waitcnt vmcnt(10)
	ds_write2_b32 v66, v34, v35 offset1:1
	ds_write2_b32 v67, v36, v37 offset1:1
	s_waitcnt vmcnt(9)
	ds_write2_b32 v68, v38, v39 offset1:1
	ds_write2_b32 v69, v40, v41 offset1:1
	s_waitcnt vmcnt(8)
	ds_write2_b32 v70, v42, v43 offset1:1
	ds_write2_b32 v71, v44, v45 offset1:1
	s_waitcnt vmcnt(7)
	ds_write2_b32 v72, v46, v47 offset1:1
	ds_write2_b32 v73, v48, v49 offset1:1
	s_waitcnt vmcnt(6)
	ds_write2_b32 v74, v106, v107 offset1:1
	ds_write2_b32 v75, v108, v109 offset1:1
	s_waitcnt vmcnt(5)
	ds_write2_b32 v76, v110, v111 offset1:1
	ds_write2_b32 v77, v112, v113 offset1:1
	s_waitcnt vmcnt(4)
	ds_write2_b32 v78, v114, v115 offset1:1
	ds_write2_b32 v79, v116, v117 offset1:1
	s_waitcnt vmcnt(3)
	ds_write2_b32 v80, v118, v119 offset1:1
	ds_write2_b32 v81, v120, v121 offset1:1
	s_waitcnt vmcnt(2)
	ds_write2_b32 v82, v122, v123 offset1:1
	ds_write2_b32 v83, v124, v125 offset1:1
	s_waitcnt vmcnt(1)
	ds_write2_b32 v84, v126, v127 offset1:1
	ds_write2_b32 v85, v128, v129 offset1:1
	s_waitcnt vmcnt(0)
	ds_write2_b32 v86, v130, v131 offset1:1
	ds_write2_b32 v87, v132, v133 offset1:1
	s_waitcnt lgkmcnt(0)
	ds_read2_b32 v[6:7], v29 offset1:8
	ds_read2_b32 v[8:9], v29 offset0:65 offset1:73
	ds_read2_b32 v[10:11], v29 offset0:130 offset1:138
	ds_read2_b32 v[12:13], v29 offset0:195 offset1:203
	ds_read2_b32 v[14:15], v88 offset0:4 offset1:12
	ds_read2_b32 v[16:17], v88 offset0:69 offset1:77
	ds_read2_b32 v[18:19], v88 offset0:134 offset1:142
	ds_read2_b32 v[20:21], v88 offset0:199 offset1:207
	v_or_b32_e32 v36, s18, v27
	v_mov_b32_e32 v37, v25
	v_lshl_add_u64 v[34:35], s[52:53], 0, v[24:25]
	v_lshlrev_b64 v[36:37], 9, v[36:37]
	s_waitcnt lgkmcnt(6)
	v_cvt_pk_bf16_f32 v2, v6, v8
	s_waitcnt lgkmcnt(4)
	v_cvt_pk_bf16_f32 v3, v10, v12
	s_waitcnt lgkmcnt(2)
	v_cvt_pk_bf16_f32 v4, v14, v16
	s_waitcnt lgkmcnt(0)
	v_cvt_pk_bf16_f32 v5, v18, v20
	v_lshl_add_u64 v[36:37], v[34:35], 0, v[36:37]
	global_store_dwordx4 v[36:37], v[2:5], off nt
	v_or_b32_e32 v6, s18, v50
	s_nop 0
	v_cvt_pk_bf16_f32 v2, v7, v9
	v_cvt_pk_bf16_f32 v3, v11, v13
	v_cvt_pk_bf16_f32 v4, v15, v17
	v_cvt_pk_bf16_f32 v5, v19, v21
	v_mov_b32_e32 v7, v25
	ds_read2_b32 v[8:9], v29 offset0:16 offset1:24
	ds_read2_b32 v[10:11], v29 offset0:81 offset1:89
	ds_read2_b32 v[12:13], v29 offset0:146 offset1:154
	ds_read2_b32 v[14:15], v29 offset0:211 offset1:219
	ds_read2_b32 v[16:17], v88 offset0:20 offset1:28
	ds_read2_b32 v[18:19], v88 offset0:85 offset1:93
	ds_read2_b32 v[20:21], v88 offset0:150 offset1:158
	ds_read2_b32 v[36:37], v88 offset0:215 offset1:223
	v_lshlrev_b64 v[6:7], 9, v[6:7]
	v_lshl_add_u64 v[6:7], v[34:35], 0, v[6:7]
	global_store_dwordx4 v[6:7], v[2:5], off nt
	v_or_b32_e32 v6, s18, v51
	v_mov_b32_e32 v7, v25
	v_lshlrev_b64 v[6:7], 9, v[6:7]
	s_waitcnt lgkmcnt(6)
	v_cvt_pk_bf16_f32 v2, v8, v10
	s_waitcnt lgkmcnt(4)
	v_cvt_pk_bf16_f32 v3, v12, v14
	s_waitcnt lgkmcnt(2)
	v_cvt_pk_bf16_f32 v4, v16, v18
	s_waitcnt lgkmcnt(0)
	v_cvt_pk_bf16_f32 v5, v20, v36
	v_lshl_add_u64 v[6:7], v[34:35], 0, v[6:7]
	global_store_dwordx4 v[6:7], v[2:5], off nt
	v_or_b32_e32 v6, s18, v52
	v_mov_b32_e32 v7, v25
	v_cvt_pk_bf16_f32 v2, v9, v11
	v_cvt_pk_bf16_f32 v3, v13, v15
	v_cvt_pk_bf16_f32 v4, v17, v19
	v_cvt_pk_bf16_f32 v5, v21, v37
	ds_read2_b32 v[8:9], v29 offset0:32 offset1:40
	ds_read2_b32 v[10:11], v29 offset0:97 offset1:105
	ds_read2_b32 v[12:13], v29 offset0:162 offset1:170
	ds_read2_b32 v[14:15], v29 offset0:227 offset1:235
	ds_read2_b32 v[16:17], v88 offset0:36 offset1:44
	ds_read2_b32 v[18:19], v88 offset0:101 offset1:109
	ds_read2_b32 v[20:21], v88 offset0:166 offset1:174
	ds_read2_b32 v[36:37], v88 offset0:231 offset1:239
	v_lshlrev_b64 v[6:7], 9, v[6:7]
	v_lshl_add_u64 v[6:7], v[34:35], 0, v[6:7]
	global_store_dwordx4 v[6:7], v[2:5], off nt
	v_or_b32_e32 v6, s18, v53
	v_mov_b32_e32 v7, v25
	v_lshlrev_b64 v[6:7], 9, v[6:7]
	s_waitcnt lgkmcnt(6)
	v_cvt_pk_bf16_f32 v2, v8, v10
	s_waitcnt lgkmcnt(4)
	v_cvt_pk_bf16_f32 v3, v12, v14
	s_waitcnt lgkmcnt(2)
	v_cvt_pk_bf16_f32 v4, v16, v18
	s_waitcnt lgkmcnt(0)
	v_cvt_pk_bf16_f32 v5, v20, v36
	v_lshl_add_u64 v[6:7], v[34:35], 0, v[6:7]
	global_store_dwordx4 v[6:7], v[2:5], off nt
	v_or_b32_e32 v6, s18, v54
	v_mov_b32_e32 v7, v25
	v_cvt_pk_bf16_f32 v2, v9, v11
	v_cvt_pk_bf16_f32 v3, v13, v15
	v_cvt_pk_bf16_f32 v4, v17, v19
	v_cvt_pk_bf16_f32 v5, v21, v37
	ds_read2_b32 v[8:9], v29 offset0:48 offset1:56
	ds_read2_b32 v[10:11], v29 offset0:113 offset1:121
	ds_read2_b32 v[12:13], v29 offset0:178 offset1:186
	ds_read2_b32 v[14:15], v29 offset0:243 offset1:251
	ds_read2_b32 v[16:17], v88 offset0:52 offset1:60
	ds_read2_b32 v[18:19], v88 offset0:117 offset1:125
	ds_read2_b32 v[20:21], v88 offset0:182 offset1:190
	ds_read2_b32 v[36:37], v88 offset0:247 offset1:255
	v_lshlrev_b64 v[6:7], 9, v[6:7]
	v_lshl_add_u64 v[6:7], v[34:35], 0, v[6:7]
	global_store_dwordx4 v[6:7], v[2:5], off nt
	v_or_b32_e32 v6, s18, v55
	v_mov_b32_e32 v7, v25
	v_lshlrev_b64 v[6:7], 9, v[6:7]
	s_waitcnt lgkmcnt(6)
	v_cvt_pk_bf16_f32 v2, v8, v10
	s_waitcnt lgkmcnt(4)
	v_cvt_pk_bf16_f32 v3, v12, v14
	s_waitcnt lgkmcnt(2)
	v_cvt_pk_bf16_f32 v4, v16, v18
	s_waitcnt lgkmcnt(0)
	v_cvt_pk_bf16_f32 v5, v20, v36
	v_lshl_add_u64 v[6:7], v[34:35], 0, v[6:7]
	global_store_dwordx4 v[6:7], v[2:5], off nt
	v_or_b32_e32 v6, s18, v56
	v_mov_b32_e32 v7, v25
	v_lshlrev_b64 v[6:7], 9, v[6:7]
	v_cvt_pk_bf16_f32 v2, v9, v11
	v_cvt_pk_bf16_f32 v3, v13, v15
	v_cvt_pk_bf16_f32 v4, v17, v19
	v_cvt_pk_bf16_f32 v5, v21, v37
	v_lshl_add_u64 v[6:7], v[34:35], 0, v[6:7]
	global_store_dwordx4 v[6:7], v[2:5], off nt
	s_waitcnt lgkmcnt(0)

.LBB0_35:
	s_andn2_b64 vcc, exec, s[18:19]
	s_cbranch_vccnz .LBB0_73
	s_add_i32 s18, s96, 0xffffb3e0
	s_lshr_b32 s19, s18, 3
	s_mul_i32 s40, s19, 0xaaab
	s_mul_i32 s18, s18, 0xaaab
	s_lshr_b32 s40, s40, 20
	s_lshr_b32 s18, s18, 16
	s_mul_i32 s40, s40, 24
	s_sub_i32 s19, s19, s40
	s_and_b32 s18, s18, 0xff80
	s_and_b32 s40, s85, 64
	s_or_b32 s55, s40, s18
	s_lshl_b32 s18, s19, 8
	s_and_b32 s18, s18, 0xff00
	s_and_b32 s19, s84, 0xc0
	s_or_b32 s54, s19, s18
	s_lshl_b32 s40, s54, 2
	v_or_b32_e32 v4, s55, v1
	s_add_u32 s18, s50, s40
	s_addc_u32 s19, s51, 0
	v_mov_b32_e32 v33, v25
	v_mul_u32_u24_e32 v4, 0x2c10, v4
	v_lshl_add_u64 v[2:3], s[18:19], 0, v[32:33]
	v_lshlrev_b32_e32 v4, 2, v4
	v_mov_b32_e32 v5, v25
	v_lshl_add_u64 v[130:131], v[2:3], 0, v[4:5]
	s_movk_i32 s18, 0x5000
	v_add_co_u32_e32 v2, vcc, s18, v130
	s_mov_b32 s18, 0x31000
	s_nop 0
	v_addc_co_u32_e32 v3, vcc, 0, v131, vcc
	s_waitcnt vmcnt(8)
	v_add_co_u32_e32 v6, vcc, s18, v130
	s_mov_b32 s18, 0x5d000
	s_nop 0
	v_addc_co_u32_e32 v7, vcc, 0, v131, vcc
	v_add_co_u32_e32 v10, vcc, s18, v130
	s_mov_b32 s18, 0x89000
	s_nop 0
	v_addc_co_u32_e32 v11, vcc, 0, v131, vcc
	v_add_co_u32_e32 v14, vcc, s18, v130
	s_mov_b32 s18, 0xb5000
	s_nop 0
	v_addc_co_u32_e32 v15, vcc, 0, v131, vcc
	v_add_co_u32_e32 v18, vcc, s18, v130
	s_mov_b32 s18, 0xe1000
	s_nop 0
	v_addc_co_u32_e32 v19, vcc, 0, v131, vcc
	v_add_co_u32_e32 v34, vcc, s18, v130
	s_mov_b32 s18, 0x10d000
	s_nop 0
	v_addc_co_u32_e32 v35, vcc, 0, v131, vcc
	s_waitcnt lgkmcnt(3)
	v_add_co_u32_e32 v38, vcc, s18, v130
	s_mov_b32 s18, 0x139000
	s_nop 0
	v_addc_co_u32_e32 v39, vcc, 0, v131, vcc
	s_waitcnt lgkmcnt(1)
	v_add_co_u32_e32 v42, vcc, s18, v130
	s_mov_b32 s18, 0x165000
	s_nop 0
	v_addc_co_u32_e32 v43, vcc, 0, v131, vcc
	s_waitcnt lgkmcnt(0)
	v_add_co_u32_e32 v46, vcc, s18, v130
	s_mov_b32 s18, 0x191000
	s_nop 0
	v_addc_co_u32_e32 v47, vcc, 0, v131, vcc
	v_add_co_u32_e32 v106, vcc, s18, v130
	s_mov_b32 s18, 0x1bd000
	s_nop 0
	v_addc_co_u32_e32 v107, vcc, 0, v131, vcc
	v_add_co_u32_e32 v110, vcc, s18, v130
	s_mov_b32 s18, 0x1e9000
	s_nop 0
	v_addc_co_u32_e32 v111, vcc, 0, v131, vcc
	v_add_co_u32_e32 v114, vcc, s18, v130
	s_mov_b32 s18, 0x215000
	s_nop 0
	v_addc_co_u32_e32 v115, vcc, 0, v131, vcc
	v_add_co_u32_e32 v118, vcc, s18, v130
	s_mov_b32 s18, 0x241000
	s_nop 0
	v_addc_co_u32_e32 v119, vcc, 0, v131, vcc
	v_add_co_u32_e32 v122, vcc, s18, v130
	global_load_dwordx4 v[2:5], v[2:3], off offset:64 nt
	s_nop 0
	global_load_dwordx4 v[6:9], v[6:7], off offset:320 nt
	v_addc_co_u32_e32 v123, vcc, 0, v131, vcc
	global_load_dwordx4 v[10:13], v[10:11], off offset:576 nt
	s_nop 0
	global_load_dwordx4 v[14:17], v[14:15], off offset:832 nt
	s_nop 0
	global_load_dwordx4 v[18:21], v[18:19], off offset:1088 nt
	s_nop 0
	global_load_dwordx4 v[34:37], v[34:35], off offset:1344 nt
	s_nop 0
	global_load_dwordx4 v[38:41], v[38:39], off offset:1600 nt
	s_nop 0
	global_load_dwordx4 v[42:45], v[42:43], off offset:1856 nt
	s_nop 0
	global_load_dwordx4 v[46:49], v[46:47], off offset:2112 nt
	s_nop 0
	global_load_dwordx4 v[106:109], v[106:107], off offset:2368 nt
	s_nop 0
	global_load_dwordx4 v[110:113], v[110:111], off offset:2624 nt
	s_nop 0
	global_load_dwordx4 v[114:117], v[114:115], off offset:2880 nt
	s_nop 0
	global_load_dwordx4 v[118:121], v[118:119], off offset:3136 nt
	s_nop 0
	global_load_dwordx4 v[122:125], v[122:123], off offset:3392 nt
	s_mov_b32 s18, 0x26d000
	v_add_co_u32_e32 v126, vcc, s18, v130
	s_mov_b32 s18, 0x299000
	s_nop 0
	v_addc_co_u32_e32 v127, vcc, 0, v131, vcc
	global_load_dwordx4 v[126:129], v[126:127], off offset:3648 nt
	v_add_co_u32_e32 v130, vcc, s18, v130
	s_nop 1
	v_addc_co_u32_e32 v131, vcc, 0, v131, vcc
	global_load_dwordx4 v[130:133], v[130:131], off offset:3904 nt
	s_andn2_b64 vcc, exec, s[38:39]
	s_waitcnt vmcnt(15)
	ds_write2_b32 v23, v2, v3 offset1:1
	ds_write2_b32 v23, v4, v5 offset0:2 offset1:3
	s_waitcnt vmcnt(14)
	ds_write2_b32 v58, v6, v7 offset1:1
	ds_write2_b32 v59, v8, v9 offset1:1
	s_waitcnt vmcnt(13)
	ds_write2_b32 v60, v10, v11 offset1:1
	ds_write2_b32 v61, v12, v13 offset1:1
	s_waitcnt vmcnt(12)
	ds_write2_b32 v62, v14, v15 offset1:1
	ds_write2_b32 v63, v16, v17 offset1:1
	s_waitcnt vmcnt(11)
	ds_write2_b32 v64, v18, v19 offset1:1
	ds_write2_b32 v65, v20, v21 offset1:1
	s_waitcnt vmcnt(10)
	ds_write2_b32 v66, v34, v35 offset1:1
	ds_write2_b32 v67, v36, v37 offset1:1
	s_waitcnt vmcnt(9)
	ds_write2_b32 v68, v38, v39 offset1:1
	ds_write2_b32 v69, v40, v41 offset1:1
	s_waitcnt vmcnt(8)
	ds_write2_b32 v70, v42, v43 offset1:1
	ds_write2_b32 v71, v44, v45 offset1:1
	s_waitcnt vmcnt(7)
	ds_write2_b32 v72, v46, v47 offset1:1
	ds_write2_b32 v73, v48, v49 offset1:1
	s_waitcnt vmcnt(6)
	ds_write2_b32 v74, v106, v107 offset1:1
	ds_write2_b32 v75, v108, v109 offset1:1
	s_waitcnt vmcnt(5)
	ds_write2_b32 v76, v110, v111 offset1:1
	ds_write2_b32 v77, v112, v113 offset1:1
	s_waitcnt vmcnt(4)
	ds_write2_b32 v78, v114, v115 offset1:1
	ds_write2_b32 v79, v116, v117 offset1:1
	s_waitcnt vmcnt(3)
	ds_write2_b32 v80, v118, v119 offset1:1
	ds_write2_b32 v81, v120, v121 offset1:1
	s_waitcnt vmcnt(2)
	ds_write2_b32 v82, v122, v123 offset1:1
	ds_write2_b32 v83, v124, v125 offset1:1
	s_waitcnt vmcnt(1)
	ds_write2_b32 v84, v126, v127 offset1:1
	ds_write2_b32 v85, v128, v129 offset1:1
	s_waitcnt vmcnt(0)
	ds_write2_b32 v86, v130, v131 offset1:1
	ds_write2_b32 v87, v132, v133 offset1:1
	s_waitcnt lgkmcnt(0)
	v_cndmask_b32_e64 v2, 0, 1, s[38:39]
	v_cmp_ne_u32_e64 s[18:19], 1, v2
	s_cbranch_vccnz .LBB0_38
	v_or_b32_e32 v2, s55, v26
	v_lshlrev_b32_e32 v14, 2, v2
	global_load_dwordx4 v[10:13], v14, s[48:49]
	global_load_dwordx4 v[2:5], v14, s[48:49] offset:16
	global_load_dwordx4 v[6:9], v14, s[46:47] offset:16
	s_nop 0
	global_load_dwordx4 v[14:17], v14, s[46:47]
	s_waitcnt vmcnt(3)
	v_mov_b32_e32 v34, v13
	s_waitcnt vmcnt(2)
	v_mov_b32_e32 v35, v2
	v_mov_b32_e32 v36, v11
	v_mov_b32_e32 v37, v12
	v_mov_b32_e32 v2, v3
	v_mov_b32_e32 v3, v4

.LBB0_74:
	s_andn2_b64 vcc, exec, s[18:19]
	s_cbranch_vccnz .LBB0_112
	s_add_i32 s18, s96, 0xffffb7e0
	s_lshr_b32 s19, s18, 5
	s_and_b32 s19, s19, 0x3fffffe
	s_bfe_u32 s40, s96, 0x10002
	s_lshr_b32 s18, s18, 1
	s_or_b32 s19, s19, s40
	s_and_b32 s18, s18, 28
	s_and_b32 s40, s96, 3
	s_or_b32 s54, s18, s40
	s_lshl_b32 s40, s19, 6
	s_lshl_b32 s18, s54, 8
	s_add_u32 s18, s50, s18
	s_addc_u32 s19, s51, 0
	v_mov_b32_e32 v33, v25
	v_or_b32_e32 v31, s40, v1
	v_lshl_add_u64 v[2:3], s[18:19], 0, v[32:33]
	s_mov_b64 s[18:19], 0x3000
	v_lshl_add_u64 v[130:131], v[2:3], 0, s[18:19]
	v_or_b32_e32 v33, 24, v31
	s_waitcnt lgkmcnt(3)
	v_mad_u64_u32 v[38:39], s[18:19], v33, s92, v[130:131]
	v_or_b32_e32 v33, 28, v31
	s_waitcnt lgkmcnt(1)
	v_mad_u64_u32 v[42:43], s[18:19], v33, s92, v[130:131]
	v_or_b32_e32 v33, 32, v31
	s_waitcnt lgkmcnt(0)
	v_mad_u64_u32 v[46:47], s[18:19], v33, s92, v[130:131]
	v_or_b32_e32 v33, 36, v31
	v_mad_u64_u32 v[106:107], s[18:19], v33, s92, v[130:131]
	v_or_b32_e32 v33, 40, v31
	v_mad_u64_u32 v[110:111], s[18:19], v33, s92, v[130:131]
	v_or_b32_e32 v33, 44, v31
	v_mad_u64_u32 v[114:115], s[18:19], v33, s92, v[130:131]
	v_or_b32_e32 v33, 48, v31
	v_or_b32_e32 v4, 4, v31
	s_waitcnt vmcnt(9)
	v_or_b32_e32 v10, 8, v31
	v_or_b32_e32 v12, 12, v31
	v_or_b32_e32 v18, 16, v31
	v_or_b32_e32 v20, 20, v31
	v_mad_u64_u32 v[118:119], s[18:19], v33, s92, v[130:131]
	v_or_b32_e32 v33, 52, v31
	v_mad_u64_u32 v[2:3], s[18:19], v31, s92, v[130:131]
	s_waitcnt vmcnt(8)
	v_mad_u64_u32 v[6:7], s[18:19], v4, s92, v[130:131]
	v_mad_u64_u32 v[10:11], s[18:19], v10, s92, v[130:131]
	s_waitcnt vmcnt(8)
	v_mad_u64_u32 v[14:15], s[18:19], v12, s92, v[130:131]
	v_mad_u64_u32 v[18:19], s[18:19], v18, s92, v[130:131]
	v_mad_u64_u32 v[34:35], s[18:19], v20, s92, v[130:131]
	v_mad_u64_u32 v[122:123], s[18:19], v33, s92, v[130:131]
	global_load_dwordx4 v[2:5], v[2:3], off nt
	s_nop 0
	global_load_dwordx4 v[6:9], v[6:7], off nt
	s_nop 0
	global_load_dwordx4 v[10:13], v[10:11], off nt
	s_nop 0
	global_load_dwordx4 v[14:17], v[14:15], off nt
	s_nop 0
	global_load_dwordx4 v[18:21], v[18:19], off nt
	s_nop 0
	global_load_dwordx4 v[34:37], v[34:35], off nt
	s_nop 0
	global_load_dwordx4 v[38:41], v[38:39], off nt
	s_nop 0
	global_load_dwordx4 v[42:45], v[42:43], off nt
	s_nop 0
	global_load_dwordx4 v[46:49], v[46:47], off nt
	s_nop 0
	global_load_dwordx4 v[106:109], v[106:107], off nt
	s_nop 0
	global_load_dwordx4 v[110:113], v[110:111], off nt
	s_nop 0
	global_load_dwordx4 v[114:117], v[114:115], off nt
	s_nop 0
	global_load_dwordx4 v[118:121], v[118:119], off nt
	s_nop 0
	global_load_dwordx4 v[122:125], v[122:123], off nt
	v_or_b32_e32 v33, 56, v31
	v_mad_u64_u32 v[126:127], s[18:19], v33, s92, v[130:131]
	global_load_dwordx4 v[126:129], v[126:127], off nt
	v_or_b32_e32 v31, 60, v31
	v_mad_u64_u32 v[130:131], s[18:19], v31, s92, v[130:131]
	global_load_dwordx4 v[130:133], v[130:131], off nt
	s_andn2_b64 vcc, exec, s[38:39]
	s_waitcnt vmcnt(15)
	ds_write2_b32 v23, v2, v3 offset1:1
	ds_write2_b32 v23, v4, v5 offset0:2 offset1:3
	s_waitcnt vmcnt(14)
	ds_write2_b32 v58, v6, v7 offset1:1
	ds_write2_b32 v59, v8, v9 offset1:1
	s_waitcnt vmcnt(13)
	ds_write2_b32 v60, v10, v11 offset1:1
	ds_write2_b32 v61, v12, v13 offset1:1
	s_waitcnt vmcnt(12)
	ds_write2_b32 v62, v14, v15 offset1:1
	ds_write2_b32 v63, v16, v17 offset1:1
	s_waitcnt vmcnt(11)
	ds_write2_b32 v64, v18, v19 offset1:1
	ds_write2_b32 v65, v20, v21 offset1:1
	s_waitcnt vmcnt(10)
	ds_write2_b32 v66, v34, v35 offset1:1
	ds_write2_b32 v67, v36, v37 offset1:1
	s_waitcnt vmcnt(9)
	ds_write2_b32 v68, v38, v39 offset1:1
	ds_write2_b32 v69, v40, v41 offset1:1
	s_waitcnt vmcnt(8)
	ds_write2_b32 v70, v42, v43 offset1:1
	ds_write2_b32 v71, v44, v45 offset1:1
	s_waitcnt vmcnt(7)
	ds_write2_b32 v72, v46, v47 offset1:1
	ds_write2_b32 v73, v48, v49 offset1:1
	s_waitcnt vmcnt(6)
	ds_write2_b32 v74, v106, v107 offset1:1
	ds_write2_b32 v75, v108, v109 offset1:1
	s_waitcnt vmcnt(5)
	ds_write2_b32 v76, v110, v111 offset1:1
	ds_write2_b32 v77, v112, v113 offset1:1
	s_waitcnt vmcnt(4)
	ds_write2_b32 v78, v114, v115 offset1:1
	ds_write2_b32 v79, v116, v117 offset1:1
	s_waitcnt vmcnt(3)
	ds_write2_b32 v80, v118, v119 offset1:1
	ds_write2_b32 v81, v120, v121 offset1:1
	s_waitcnt vmcnt(2)
	ds_write2_b32 v82, v122, v123 offset1:1
	ds_write2_b32 v83, v124, v125 offset1:1
	s_waitcnt vmcnt(1)
	ds_write2_b32 v84, v126, v127 offset1:1
	ds_write2_b32 v85, v128, v129 offset1:1
	s_waitcnt vmcnt(0)
	ds_write2_b32 v86, v130, v131 offset1:1
	ds_write2_b32 v87, v132, v133 offset1:1
	s_waitcnt lgkmcnt(0)
	v_cndmask_b32_e64 v2, 0, 1, s[38:39]
	v_cmp_ne_u32_e64 s[18:19], 1, v2
	s_cbranch_vccnz .LBB0_77
	v_or_b32_e32 v2, s40, v26
	v_mov_b32_e32 v3, v25
	v_lshlrev_b64 v[10:11], 2, v[2:3]
	v_lshl_add_u64 v[2:3], s[48:49], 0, v[10:11]
	global_load_dwordx4 v[6:9], v[2:3], off nt
	s_nop 0
	global_load_dwordx4 v[2:5], v[2:3], off offset:16 nt
	v_lshl_add_u64 v[14:15], s[46:47], 0, v[10:11]
	global_load_dwordx4 v[10:13], v[14:15], off offset:16 nt
	s_nop 0
	global_load_dwordx4 v[14:17], v[14:15], off nt
	s_waitcnt vmcnt(3)
	v_mov_b32_e32 v34, v9
	s_waitcnt vmcnt(2)
	v_mov_b32_e32 v35, v2
	v_mov_b32_e32 v36, v7
	v_mov_b32_e32 v37, v8
	v_mov_b32_e32 v2, v3
	v_mov_b32_e32 v3, v4

.LBB0_113:
	s_andn2_b64 vcc, exec, s[18:19]
	s_cbranch_vccnz .LBB0_151
	s_mul_i32 s40, s42, 0xffe7d800
	s_add_i32 s40, s40, s84
	v_mov_b32_e32 v33, v25
	v_add_u32_e32 v31, s40, v1
	v_lshl_add_u64 v[2:3], s[50:51], 0, v[32:33]
	s_mov_b64 s[18:19], 0x5000
	v_lshl_add_u64 v[130:131], v[2:3], 0, s[18:19]
	v_add_u32_e32 v33, 0xffee0018, v31
	s_waitcnt lgkmcnt(3)
	v_mad_u64_u32 v[38:39], s[18:19], v33, s92, v[130:131]
	v_add_u32_e32 v33, 0xffee001c, v31
	s_waitcnt lgkmcnt(1)
	v_mad_u64_u32 v[42:43], s[18:19], v33, s92, v[130:131]
	v_add_u32_e32 v33, 0xffee0020, v31
	s_waitcnt lgkmcnt(0)
	v_mad_u64_u32 v[46:47], s[18:19], v33, s92, v[130:131]
	v_add_u32_e32 v33, 0xffee0024, v31
	v_mad_u64_u32 v[106:107], s[18:19], v33, s92, v[130:131]
	v_add_u32_e32 v33, 0xffee0028, v31
	v_mad_u64_u32 v[110:111], s[18:19], v33, s92, v[130:131]
	v_add_u32_e32 v33, 0xffee002c, v31
	v_add_u32_e32 v4, 0xffee0000, v31
	v_mad_u64_u32 v[114:115], s[18:19], v33, s92, v[130:131]
	v_add_u32_e32 v33, 0xffee0030, v31
	v_mad_u64_u32 v[2:3], s[18:19], v4, s92, v[130:131]
	v_add_u32_e32 v4, 0xffee0004, v31
	s_waitcnt vmcnt(9)
	v_add_u32_e32 v10, 0xffee0008, v31
	v_add_u32_e32 v12, 0xffee000c, v31
	v_add_u32_e32 v18, 0xffee0010, v31
	v_add_u32_e32 v20, 0xffee0014, v31
	v_mad_u64_u32 v[118:119], s[18:19], v33, s92, v[130:131]
	v_add_u32_e32 v33, 0xffee0034, v31
	s_waitcnt vmcnt(8)
	v_mad_u64_u32 v[6:7], s[18:19], v4, s92, v[130:131]
	v_mad_u64_u32 v[10:11], s[18:19], v10, s92, v[130:131]
	s_waitcnt vmcnt(8)
	v_mad_u64_u32 v[14:15], s[18:19], v12, s92, v[130:131]
	v_mad_u64_u32 v[18:19], s[18:19], v18, s92, v[130:131]
	v_mad_u64_u32 v[34:35], s[18:19], v20, s92, v[130:131]
	v_mad_u64_u32 v[122:123], s[18:19], v33, s92, v[130:131]
	global_load_dwordx4 v[2:5], v[2:3], off nt
	s_nop 0
	global_load_dwordx4 v[6:9], v[6:7], off nt
	s_nop 0
	global_load_dwordx4 v[10:13], v[10:11], off nt
	s_nop 0
	global_load_dwordx4 v[14:17], v[14:15], off nt
	s_nop 0
	global_load_dwordx4 v[18:21], v[18:19], off nt
	s_nop 0
	global_load_dwordx4 v[34:37], v[34:35], off nt
	s_nop 0
	global_load_dwordx4 v[38:41], v[38:39], off nt
	s_nop 0
	global_load_dwordx4 v[42:45], v[42:43], off nt
	s_nop 0
	global_load_dwordx4 v[46:49], v[46:47], off nt
	s_nop 0
	global_load_dwordx4 v[106:109], v[106:107], off nt
	s_nop 0
	global_load_dwordx4 v[110:113], v[110:111], off nt
	s_nop 0
	global_load_dwordx4 v[114:117], v[114:115], off nt
	s_nop 0
	global_load_dwordx4 v[118:121], v[118:119], off nt
	s_nop 0
	global_load_dwordx4 v[122:125], v[122:123], off nt
	v_add_u32_e32 v33, 0xffee0038, v31
	v_mad_u64_u32 v[126:127], s[18:19], v33, s92, v[130:131]
	global_load_dwordx4 v[126:129], v[126:127], off nt
	v_add_u32_e32 v31, 0xffee003c, v31
	v_mad_u64_u32 v[130:131], s[18:19], v31, s92, v[130:131]
	global_load_dwordx4 v[130:133], v[130:131], off nt
	s_andn2_b64 vcc, exec, s[38:39]
	s_waitcnt vmcnt(15)
	ds_write2_b32 v23, v2, v3 offset1:1
	ds_write2_b32 v23, v4, v5 offset0:2 offset1:3
	s_waitcnt vmcnt(14)
	ds_write2_b32 v58, v6, v7 offset1:1
	ds_write2_b32 v59, v8, v9 offset1:1
	s_waitcnt vmcnt(13)
	ds_write2_b32 v60, v10, v11 offset1:1
	ds_write2_b32 v61, v12, v13 offset1:1
	s_waitcnt vmcnt(12)
	ds_write2_b32 v62, v14, v15 offset1:1
	ds_write2_b32 v63, v16, v17 offset1:1
	s_waitcnt vmcnt(11)
	ds_write2_b32 v64, v18, v19 offset1:1
	ds_write2_b32 v65, v20, v21 offset1:1
	s_waitcnt vmcnt(10)
	ds_write2_b32 v66, v34, v35 offset1:1
	ds_write2_b32 v67, v36, v37 offset1:1
	s_waitcnt vmcnt(9)
	ds_write2_b32 v68, v38, v39 offset1:1
	ds_write2_b32 v69, v40, v41 offset1:1
	s_waitcnt vmcnt(8)
	ds_write2_b32 v70, v42, v43 offset1:1
	ds_write2_b32 v71, v44, v45 offset1:1
	s_waitcnt vmcnt(7)
	ds_write2_b32 v72, v46, v47 offset1:1
	ds_write2_b32 v73, v48, v49 offset1:1
	s_waitcnt vmcnt(6)
	ds_write2_b32 v74, v106, v107 offset1:1
	ds_write2_b32 v75, v108, v109 offset1:1
	s_waitcnt vmcnt(5)
	ds_write2_b32 v76, v110, v111 offset1:1
	ds_write2_b32 v77, v112, v113 offset1:1
	s_waitcnt vmcnt(4)
	ds_write2_b32 v78, v114, v115 offset1:1
	ds_write2_b32 v79, v116, v117 offset1:1
	s_waitcnt vmcnt(3)
	ds_write2_b32 v80, v118, v119 offset1:1
	ds_write2_b32 v81, v120, v121 offset1:1
	s_waitcnt vmcnt(2)
	ds_write2_b32 v82, v122, v123 offset1:1
	ds_write2_b32 v83, v124, v125 offset1:1
	s_waitcnt vmcnt(1)
	ds_write2_b32 v84, v126, v127 offset1:1
	ds_write2_b32 v85, v128, v129 offset1:1
	s_waitcnt vmcnt(0)
	ds_write2_b32 v86, v130, v131 offset1:1
	ds_write2_b32 v87, v132, v133 offset1:1
	s_waitcnt lgkmcnt(0)
	v_cndmask_b32_e64 v2, 0, 1, s[38:39]
	v_cmp_ne_u32_e64 s[18:19], 1, v2
	s_cbranch_vccnz .LBB0_116
	v_add_u32_e32 v2, s40, v57
	v_mov_b32_e32 v3, v25
	v_lshlrev_b64 v[4:5], 2, v[2:3]
	v_ashrrev_i32_e32 v3, 31, v2
	v_lshl_add_u64 v[6:7], s[46:47], 0, v[4:5]
	v_lshlrev_b64 v[2:3], 2, v[2:3]
	v_lshl_add_u64 v[4:5], s[48:49], 0, v[4:5]
	global_load_dwordx2 v[20:21], v[6:7], off
	v_lshl_add_u64 v[6:7], s[48:49], 0, v[2:3]
	v_lshl_add_u64 v[8:9], s[46:47], 0, v[2:3]
	global_load_dwordx3 v[14:16], v[6:7], off offset:20
	global_load_dword v17, v[4:5], off
	s_nop 0
	global_load_dwordx4 v[2:5], v[6:7], off offset:4 nt
	global_load_dwordx2 v[18:19], v[8:9], off offset:24
	s_nop 0
	global_load_dwordx4 v[6:9], v[8:9], off offset:8 nt

.LBB0_152:
	s_andn2_b64 vcc, exec, s[18:19]
	s_cbranch_vccnz .LBB0_190
	s_add_i32 s18, s96, 0xffffbe00
	s_lshr_b32 s19, s18, 3
	s_mul_i32 s40, s19, 0xab
	s_bfe_u32 s40, s40, 0x5000b
	s_mul_i32 s18, s18, 0xaaab
	s_mul_i32 s40, s40, 12
	s_sub_i32 s19, s19, s40
	s_lshr_b32 s18, s18, 15
	s_and_b32 s19, s19, 0xff
	s_and_b32 s18, s18, 0x1ff80
	s_and_b32 s40, s85, 64
	s_or_b32 s52, s18, s40
	s_lshl_b32 s18, s19, 8
	s_and_b32 s19, s84, 0xc0
	s_or_b32 s43, s18, s19
	s_lshl_b32 s40, s43, 2
	s_add_u32 s18, s50, s40
	v_or_b32_e32 v4, s52, v1
	s_addc_u32 s19, s51, 0
	v_mov_b32_e32 v33, v25
	v_lshl_add_u64 v[2:3], s[18:19], 0, v[32:33]
	v_mul_u32_u24_e32 v4, 0x2c10, v4
	v_mov_b32_e32 v5, v25
	v_lshl_add_u64 v[130:131], v[4:5], 2, v[2:3]
	s_mov_b32 s18, 0x2c000
	s_waitcnt vmcnt(8)
	v_add_co_u32_e32 v6, vcc, s18, v130
	s_mov_b32 s18, 0x84000
	s_nop 0
	v_addc_co_u32_e32 v7, vcc, 0, v131, vcc
	v_add_co_u32_e32 v10, vcc, s93, v130
	global_load_dwordx4 v[2:5], v[130:131], off nt
	s_nop 0
	global_load_dwordx4 v[6:9], v[6:7], off offset:256 nt
	v_addc_co_u32_e32 v11, vcc, 0, v131, vcc
	v_add_co_u32_e32 v14, vcc, s18, v130
	s_mov_b32 s18, 0xb0000
	s_nop 0
	v_addc_co_u32_e32 v15, vcc, 0, v131, vcc
	v_add_co_u32_e32 v18, vcc, s18, v130
	s_mov_b32 s18, 0xdc000
	s_nop 0
	v_addc_co_u32_e32 v19, vcc, 0, v131, vcc
	v_add_co_u32_e32 v34, vcc, s18, v130
	s_mov_b32 s18, 0x108000
	s_nop 0
	v_addc_co_u32_e32 v35, vcc, 0, v131, vcc
	s_waitcnt lgkmcnt(3)
	v_add_co_u32_e32 v38, vcc, s18, v130
	s_mov_b32 s18, 0x134000
	s_nop 0
	v_addc_co_u32_e32 v39, vcc, 0, v131, vcc
	s_waitcnt lgkmcnt(1)
	v_add_co_u32_e32 v42, vcc, s18, v130
	s_mov_b32 s18, 0x160000
	s_nop 0
	v_addc_co_u32_e32 v43, vcc, 0, v131, vcc
	s_waitcnt lgkmcnt(0)
	v_add_co_u32_e32 v46, vcc, s18, v130
	s_mov_b32 s18, 0x18c000
	s_nop 0
	v_addc_co_u32_e32 v47, vcc, 0, v131, vcc
	v_add_co_u32_e32 v106, vcc, s18, v130
	s_mov_b32 s18, 0x1b8000
	s_nop 0
	v_addc_co_u32_e32 v107, vcc, 0, v131, vcc
	v_add_co_u32_e32 v110, vcc, s18, v130
	s_mov_b32 s18, 0x1e4000
	s_nop 0
	v_addc_co_u32_e32 v111, vcc, 0, v131, vcc
	v_add_co_u32_e32 v114, vcc, s18, v130
	s_mov_b32 s18, 0x210000
	s_nop 0
	v_addc_co_u32_e32 v115, vcc, 0, v131, vcc
	v_add_co_u32_e32 v118, vcc, s18, v130
	s_mov_b32 s18, 0x23c000
	s_nop 0
	v_addc_co_u32_e32 v119, vcc, 0, v131, vcc
	v_add_co_u32_e32 v122, vcc, s18, v130
	global_load_dwordx4 v[10:13], v[10:11], off offset:512 nt
	s_nop 0
	global_load_dwordx4 v[14:17], v[14:15], off offset:768 nt
	v_addc_co_u32_e32 v123, vcc, 0, v131, vcc
	global_load_dwordx4 v[18:21], v[18:19], off offset:1024 nt
	s_nop 0
	global_load_dwordx4 v[34:37], v[34:35], off offset:1280 nt
	s_nop 0
	global_load_dwordx4 v[38:41], v[38:39], off offset:1536 nt
	s_nop 0
	global_load_dwordx4 v[42:45], v[42:43], off offset:1792 nt
	s_nop 0
	global_load_dwordx4 v[46:49], v[46:47], off offset:2048 nt
	s_nop 0
	global_load_dwordx4 v[106:109], v[106:107], off offset:2304 nt
	s_nop 0
	global_load_dwordx4 v[110:113], v[110:111], off offset:2560 nt
	s_nop 0
	global_load_dwordx4 v[114:117], v[114:115], off offset:2816 nt
	s_nop 0
	global_load_dwordx4 v[118:121], v[118:119], off offset:3072 nt
	s_nop 0
	global_load_dwordx4 v[122:125], v[122:123], off offset:3328 nt
	s_mov_b32 s18, 0x268000
	v_add_co_u32_e32 v126, vcc, s18, v130
	s_mov_b32 s18, 0x294000
	s_nop 0
	v_addc_co_u32_e32 v127, vcc, 0, v131, vcc
	global_load_dwordx4 v[126:129], v[126:127], off offset:3584 nt
	v_add_co_u32_e32 v130, vcc, s18, v130
	s_nop 1
	v_addc_co_u32_e32 v131, vcc, 0, v131, vcc
	global_load_dwordx4 v[130:133], v[130:131], off offset:3840 nt
	s_andn2_b64 vcc, exec, s[38:39]
	s_waitcnt vmcnt(15)
	ds_write2_b32 v23, v2, v3 offset1:1
	ds_write2_b32 v23, v4, v5 offset0:2 offset1:3
	s_waitcnt vmcnt(14)
	ds_write2_b32 v58, v6, v7 offset1:1
	ds_write2_b32 v59, v8, v9 offset1:1
	s_waitcnt vmcnt(13)
	ds_write2_b32 v60, v10, v11 offset1:1
	ds_write2_b32 v61, v12, v13 offset1:1
	s_waitcnt vmcnt(12)
	ds_write2_b32 v62, v14, v15 offset1:1
	ds_write2_b32 v63, v16, v17 offset1:1
	s_waitcnt vmcnt(11)
	ds_write2_b32 v64, v18, v19 offset1:1
	ds_write2_b32 v65, v20, v21 offset1:1
	s_waitcnt vmcnt(10)
	ds_write2_b32 v66, v34, v35 offset1:1
	ds_write2_b32 v67, v36, v37 offset1:1
	s_waitcnt vmcnt(9)
	ds_write2_b32 v68, v38, v39 offset1:1
	ds_write2_b32 v69, v40, v41 offset1:1
	s_waitcnt vmcnt(8)
	ds_write2_b32 v70, v42, v43 offset1:1
	ds_write2_b32 v71, v44, v45 offset1:1
	s_waitcnt vmcnt(7)
	ds_write2_b32 v72, v46, v47 offset1:1
	ds_write2_b32 v73, v48, v49 offset1:1
	s_waitcnt vmcnt(6)
	ds_write2_b32 v74, v106, v107 offset1:1
	ds_write2_b32 v75, v108, v109 offset1:1
	s_waitcnt vmcnt(5)
	ds_write2_b32 v76, v110, v111 offset1:1
	ds_write2_b32 v77, v112, v113 offset1:1
	s_waitcnt vmcnt(4)
	ds_write2_b32 v78, v114, v115 offset1:1
	ds_write2_b32 v79, v116, v117 offset1:1
	s_waitcnt vmcnt(3)
	ds_write2_b32 v80, v118, v119 offset1:1
	ds_write2_b32 v81, v120, v121 offset1:1
	s_waitcnt vmcnt(2)
	ds_write2_b32 v82, v122, v123 offset1:1
	ds_write2_b32 v83, v124, v125 offset1:1
	s_waitcnt vmcnt(1)
	ds_write2_b32 v84, v126, v127 offset1:1
	ds_write2_b32 v85, v128, v129 offset1:1
	s_waitcnt vmcnt(0)
	ds_write2_b32 v86, v130, v131 offset1:1
	ds_write2_b32 v87, v132, v133 offset1:1
	s_waitcnt lgkmcnt(0)
	v_cndmask_b32_e64 v2, 0, 1, s[38:39]
	v_cmp_ne_u32_e64 s[18:19], 1, v2
	s_cbranch_vccnz .LBB0_155
	v_or_b32_e32 v2, s52, v26
	v_lshlrev_b32_e32 v14, 2, v2
	global_load_dwordx4 v[10:13], v14, s[48:49]
	global_load_dwordx4 v[2:5], v14, s[48:49] offset:16
	global_load_dwordx4 v[6:9], v14, s[46:47] offset:16
	s_nop 0
	global_load_dwordx4 v[14:17], v14, s[46:47]
	s_waitcnt vmcnt(3)
	v_mov_b32_e32 v34, v13
	s_waitcnt vmcnt(2)
	v_mov_b32_e32 v35, v2
	v_mov_b32_e32 v36, v11
	v_mov_b32_e32 v37, v12
	v_mov_b32_e32 v2, v3
	v_mov_b32_e32 v3, v4

.LBB0_191:
	s_andn2_b64 vcc, exec, s[18:19]
	s_cbranch_vccnz .LBB0_193
	s_add_i32 s40, s96, 0xffffd400
	s_cmpk_gt_u32 s40, 0xaff
	s_cselect_b64 s[18:19], -1, 0
	v_cndmask_b32_e64 v2, 0, 1, s[18:19]
	s_add_i32 s18, s96, 0xffffc900
	s_cmpk_lt_u32 s40, 0xb00
	s_cselect_b32 s18, s40, s18
	s_lshr_b32 s19, s18, 5
	s_and_b32 s19, s19, 0x7e
	s_bfe_u32 s40, s18, 0x10002
	s_or_b32 s19, s19, s40
	s_lshr_b32 s40, s18, 1
	s_and_b32 s40, s40, 28
	s_and_b32 s18, s18, 3
	s_or_b32 s40, s40, s18
	s_lshl_b32 s18, s42, 1
	v_readfirstlane_b32 s43, v2
	s_or_b32 s43, s18, s43
	s_mul_i32 s44, s43, 0x2c00000
	s_mul_hi_i32 s18, s43, 0x2c00000
	s_add_u32 s44, s25, s44
	s_addc_u32 s45, s27, s18
	s_lshl_b32 s18, s40, 6
	s_mul_hi_i32 s46, s43, 0x1600000
	s_mul_i32 s43, s43, 0x1600000
	s_add_u32 s43, s78, s43
	s_addc_u32 s46, s79, s46
	s_lshl_b32 s40, s40, 8
	s_add_u32 s44, s44, s40
	s_addc_u32 s45, s45, 0
	v_mov_b32_e32 v33, v25
	v_lshlrev_b32_e32 v4, 13, v1
	v_lshl_add_u64 v[2:3], s[44:45], 0, v[32:33]
	v_lshl_or_b32 v4, s19, 19, v4
	v_mov_b32_e32 v5, v25
	v_lshl_add_u64 v[130:131], v[2:3], 0, v[4:5]
	s_waitcnt vmcnt(8)
	v_add_co_u32_e32 v6, vcc, s90, v130
	s_mov_b32 s40, 0x20000
	s_nop 0
	v_addc_co_u32_e32 v7, vcc, 0, v131, vcc
	v_add_co_u32_e32 v10, vcc, s91, v130
	global_load_dwordx4 v[2:5], v[130:131], off nt
	s_nop 0
	global_load_dwordx4 v[6:9], v[6:7], off nt
	v_addc_co_u32_e32 v11, vcc, 0, v131, vcc
	v_add_co_u32_e32 v14, vcc, s97, v130
	s_lshl_b32 s19, s19, 7
	s_nop 0
	v_addc_co_u32_e32 v15, vcc, 0, v131, vcc
	v_add_co_u32_e32 v18, vcc, s40, v130
	s_mov_b32 s40, 0x28000
	s_nop 0
	v_addc_co_u32_e32 v19, vcc, 0, v131, vcc
	v_add_co_u32_e32 v34, vcc, s40, v130
	s_mov_b32 s40, 0x30000
	s_nop 0
	v_addc_co_u32_e32 v35, vcc, 0, v131, vcc
	s_waitcnt lgkmcnt(3)
	v_add_co_u32_e32 v38, vcc, s40, v130
	s_mov_b32 s40, 0x38000
	s_nop 0
	v_addc_co_u32_e32 v39, vcc, 0, v131, vcc
	s_waitcnt lgkmcnt(1)
	v_add_co_u32_e32 v42, vcc, s40, v130
	s_mov_b32 s40, 0x40000
	s_nop 0
	v_addc_co_u32_e32 v43, vcc, 0, v131, vcc
	s_waitcnt lgkmcnt(0)
	v_add_co_u32_e32 v46, vcc, s40, v130
	s_mov_b32 s40, 0x48000
	s_nop 0
	v_addc_co_u32_e32 v47, vcc, 0, v131, vcc
	v_add_co_u32_e32 v106, vcc, s40, v130
	s_mov_b32 s40, 0x50000
	s_nop 0
	v_addc_co_u32_e32 v107, vcc, 0, v131, vcc
	v_add_co_u32_e32 v110, vcc, s40, v130
	s_mov_b32 s40, 0x60000
	s_nop 0
	v_addc_co_u32_e32 v111, vcc, 0, v131, vcc
	v_add_co_u32_e32 v114, vcc, s93, v130
	global_load_dwordx4 v[10:13], v[10:11], off nt
	s_nop 0
	global_load_dwordx4 v[14:17], v[14:15], off nt
	v_addc_co_u32_e32 v115, vcc, 0, v131, vcc
	v_add_co_u32_e32 v118, vcc, s40, v130
	s_mov_b32 s40, 0x68000
	s_nop 0
	v_addc_co_u32_e32 v119, vcc, 0, v131, vcc
	v_add_co_u32_e32 v122, vcc, s40, v130
	global_load_dwordx4 v[18:21], v[18:19], off nt
	s_nop 0
	global_load_dwordx4 v[34:37], v[34:35], off nt
	v_addc_co_u32_e32 v123, vcc, 0, v131, vcc
	global_load_dwordx4 v[38:41], v[38:39], off nt
	s_nop 0
	global_load_dwordx4 v[42:45], v[42:43], off nt
	s_nop 0
	global_load_dwordx4 v[46:49], v[46:47], off nt
	s_nop 0
	global_load_dwordx4 v[106:109], v[106:107], off nt
	s_nop 0
	global_load_dwordx4 v[110:113], v[110:111], off nt
	s_nop 0
	global_load_dwordx4 v[114:117], v[114:115], off nt
	s_nop 0
	global_load_dwordx4 v[118:121], v[118:119], off nt
	s_nop 0
	global_load_dwordx4 v[122:125], v[122:123], off nt
	s_mov_b32 s40, 0x70000
	v_add_co_u32_e32 v126, vcc, s40, v130
	s_mov_b32 s40, 0x78000
	s_nop 0
	v_addc_co_u32_e32 v127, vcc, 0, v131, vcc
	global_load_dwordx4 v[126:129], v[126:127], off nt
	v_add_co_u32_e32 v130, vcc, s40, v130
	s_add_u32 s44, s43, s19
	s_nop 0
	v_addc_co_u32_e32 v131, vcc, 0, v131, vcc
	global_load_dwordx4 v[130:133], v[130:131], off nt
	s_addc_u32 s45, s46, 0
	s_waitcnt vmcnt(15)
	ds_write2_b32 v23, v2, v3 offset1:1
	ds_write2_b32 v23, v4, v5 offset0:2 offset1:3
	s_waitcnt vmcnt(14)
	ds_write2_b32 v58, v6, v7 offset1:1
	ds_write2_b32 v59, v8, v9 offset1:1
	s_waitcnt vmcnt(13)
	ds_write2_b32 v60, v10, v11 offset1:1
	ds_write2_b32 v61, v12, v13 offset1:1
	s_waitcnt vmcnt(12)
	ds_write2_b32 v62, v14, v15 offset1:1
	ds_write2_b32 v63, v16, v17 offset1:1
	s_waitcnt vmcnt(11)
	ds_write2_b32 v64, v18, v19 offset1:1
	ds_write2_b32 v65, v20, v21 offset1:1
	s_waitcnt vmcnt(10)
	ds_write2_b32 v66, v34, v35 offset1:1
	ds_write2_b32 v67, v36, v37 offset1:1
	s_waitcnt vmcnt(9)
	ds_write2_b32 v68, v38, v39 offset1:1
	ds_write2_b32 v69, v40, v41 offset1:1
	s_waitcnt vmcnt(8)
	ds_write2_b32 v70, v42, v43 offset1:1
	ds_write2_b32 v71, v44, v45 offset1:1
	s_waitcnt vmcnt(7)
	ds_write2_b32 v72, v46, v47 offset1:1
	ds_write2_b32 v73, v48, v49 offset1:1
	s_waitcnt vmcnt(6)
	ds_write2_b32 v74, v106, v107 offset1:1
	ds_write2_b32 v75, v108, v109 offset1:1
	s_waitcnt vmcnt(5)
	ds_write2_b32 v76, v110, v111 offset1:1
	ds_write2_b32 v77, v112, v113 offset1:1
	s_waitcnt vmcnt(4)
	ds_write2_b32 v78, v114, v115 offset1:1
	ds_write2_b32 v79, v116, v117 offset1:1
	s_waitcnt vmcnt(3)
	ds_write2_b32 v80, v118, v119 offset1:1
	ds_write2_b32 v81, v120, v121 offset1:1
	s_waitcnt vmcnt(2)
	ds_write2_b32 v82, v122, v123 offset1:1
	ds_write2_b32 v83, v124, v125 offset1:1
	s_waitcnt vmcnt(1)
	ds_write2_b32 v84, v126, v127 offset1:1
	ds_write2_b32 v85, v128, v129 offset1:1
	s_waitcnt vmcnt(0)
	ds_write2_b32 v86, v130, v131 offset1:1
	ds_write2_b32 v87, v132, v133 offset1:1
	s_waitcnt lgkmcnt(0)
	ds_read2_b32 v[6:7], v29 offset1:8
	ds_read2_b32 v[8:9], v29 offset0:65 offset1:73
	ds_read2_b32 v[10:11], v29 offset0:130 offset1:138
	ds_read2_b32 v[12:13], v29 offset0:195 offset1:203
	ds_read2_b32 v[14:15], v88 offset0:4 offset1:12
	ds_read2_b32 v[16:17], v88 offset0:69 offset1:77
	ds_read2_b32 v[18:19], v88 offset0:134 offset1:142
	ds_read2_b32 v[20:21], v88 offset0:199 offset1:207
	s_waitcnt lgkmcnt(6)
	v_cvt_pk_bf16_f32 v2, v6, v8
	v_or_b32_e32 v6, s18, v27
	v_mul_u32_u24_e32 v6, 0x1600, v6
	v_lshl_add_u64 v[34:35], s[44:45], 0, v[24:25]
	v_lshlrev_b32_e32 v36, 1, v6
	v_mov_b32_e32 v37, v25
	s_waitcnt lgkmcnt(4)
	v_cvt_pk_bf16_f32 v3, v10, v12
	s_waitcnt lgkmcnt(2)
	v_cvt_pk_bf16_f32 v4, v14, v16
	s_waitcnt lgkmcnt(0)
	v_cvt_pk_bf16_f32 v5, v18, v20
	v_lshl_add_u64 v[36:37], v[34:35], 0, v[36:37]
	v_or_b32_e32 v6, s18, v50
	global_store_dwordx4 v[36:37], v[2:5], off nt
	v_mul_u32_u24_e32 v6, 0x1600, v6
	v_lshlrev_b32_e32 v6, 1, v6
	v_cvt_pk_bf16_f32 v2, v7, v9
	v_cvt_pk_bf16_f32 v3, v11, v13
	v_cvt_pk_bf16_f32 v4, v15, v17
	v_cvt_pk_bf16_f32 v5, v19, v21
	v_mov_b32_e32 v7, v25
	ds_read2_b32 v[8:9], v29 offset0:16 offset1:24
	ds_read2_b32 v[10:11], v29 offset0:81 offset1:89
	ds_read2_b32 v[12:13], v29 offset0:146 offset1:154
	ds_read2_b32 v[14:15], v29 offset0:211 offset1:219
	ds_read2_b32 v[16:17], v88 offset0:20 offset1:28
	ds_read2_b32 v[18:19], v88 offset0:85 offset1:93
	ds_read2_b32 v[20:21], v88 offset0:150 offset1:158
	ds_read2_b32 v[36:37], v88 offset0:215 offset1:223
	v_lshl_add_u64 v[6:7], v[34:35], 0, v[6:7]
	global_store_dwordx4 v[6:7], v[2:5], off nt
	v_or_b32_e32 v6, s18, v51
	v_mul_u32_u24_e32 v6, 0x1600, v6
	v_lshlrev_b32_e32 v6, 1, v6
	v_mov_b32_e32 v7, v25
	s_waitcnt lgkmcnt(6)
	v_cvt_pk_bf16_f32 v2, v8, v10
	s_waitcnt lgkmcnt(4)
	v_cvt_pk_bf16_f32 v3, v12, v14
	s_waitcnt lgkmcnt(2)
	v_cvt_pk_bf16_f32 v4, v16, v18
	s_waitcnt lgkmcnt(0)
	v_cvt_pk_bf16_f32 v5, v20, v36
	v_lshl_add_u64 v[6:7], v[34:35], 0, v[6:7]
	global_store_dwordx4 v[6:7], v[2:5], off nt
	v_or_b32_e32 v6, s18, v52
	v_mul_u32_u24_e32 v6, 0x1600, v6
	v_cvt_pk_bf16_f32 v2, v9, v11
	v_cvt_pk_bf16_f32 v3, v13, v15
	v_cvt_pk_bf16_f32 v4, v17, v19
	v_cvt_pk_bf16_f32 v5, v21, v37
	v_lshlrev_b32_e32 v6, 1, v6
	v_mov_b32_e32 v7, v25
	ds_read2_b32 v[8:9], v29 offset0:32 offset1:40
	ds_read2_b32 v[10:11], v29 offset0:97 offset1:105
	ds_read2_b32 v[12:13], v29 offset0:162 offset1:170
	ds_read2_b32 v[14:15], v29 offset0:227 offset1:235
	ds_read2_b32 v[16:17], v88 offset0:36 offset1:44
	ds_read2_b32 v[18:19], v88 offset0:101 offset1:109
	ds_read2_b32 v[20:21], v88 offset0:166 offset1:174
	ds_read2_b32 v[36:37], v88 offset0:231 offset1:239
	v_lshl_add_u64 v[6:7], v[34:35], 0, v[6:7]
	global_store_dwordx4 v[6:7], v[2:5], off nt
	v_or_b32_e32 v6, s18, v53
	v_mul_u32_u24_e32 v6, 0x1600, v6
	v_lshlrev_b32_e32 v6, 1, v6
	v_mov_b32_e32 v7, v25
	s_waitcnt lgkmcnt(6)
	v_cvt_pk_bf16_f32 v2, v8, v10
	s_waitcnt lgkmcnt(4)
	v_cvt_pk_bf16_f32 v3, v12, v14
	s_waitcnt lgkmcnt(2)
	v_cvt_pk_bf16_f32 v4, v16, v18
	s_waitcnt lgkmcnt(0)
	v_cvt_pk_bf16_f32 v5, v20, v36
	v_lshl_add_u64 v[6:7], v[34:35], 0, v[6:7]
	global_store_dwordx4 v[6:7], v[2:5], off nt
	v_or_b32_e32 v6, s18, v54
	v_mul_u32_u24_e32 v6, 0x1600, v6
	v_cvt_pk_bf16_f32 v2, v9, v11
	v_cvt_pk_bf16_f32 v3, v13, v15
	v_cvt_pk_bf16_f32 v4, v17, v19
	v_cvt_pk_bf16_f32 v5, v21, v37
	v_lshlrev_b32_e32 v6, 1, v6
	v_mov_b32_e32 v7, v25
	ds_read2_b32 v[8:9], v29 offset0:48 offset1:56
	ds_read2_b32 v[10:11], v29 offset0:113 offset1:121
	ds_read2_b32 v[12:13], v29 offset0:178 offset1:186
	ds_read2_b32 v[14:15], v29 offset0:243 offset1:251
	ds_read2_b32 v[16:17], v88 offset0:52 offset1:60
	ds_read2_b32 v[18:19], v88 offset0:117 offset1:125
	ds_read2_b32 v[20:21], v88 offset0:182 offset1:190
	ds_read2_b32 v[36:37], v88 offset0:247 offset1:255
	v_lshl_add_u64 v[6:7], v[34:35], 0, v[6:7]
	global_store_dwordx4 v[6:7], v[2:5], off nt
	v_or_b32_e32 v6, s18, v55
	v_mul_u32_u24_e32 v6, 0x1600, v6
	v_lshlrev_b32_e32 v6, 1, v6
	v_mov_b32_e32 v7, v25
	s_waitcnt lgkmcnt(6)
	v_cvt_pk_bf16_f32 v2, v8, v10
	s_waitcnt lgkmcnt(4)
	v_cvt_pk_bf16_f32 v3, v12, v14
	s_waitcnt lgkmcnt(2)
	v_cvt_pk_bf16_f32 v4, v16, v18
	s_waitcnt lgkmcnt(0)
	v_cvt_pk_bf16_f32 v5, v20, v36
	v_lshl_add_u64 v[6:7], v[34:35], 0, v[6:7]
	global_store_dwordx4 v[6:7], v[2:5], off nt
	v_or_b32_e32 v6, s18, v56
	v_mul_u32_u24_e32 v6, 0x1600, v6
	v_lshlrev_b32_e32 v6, 1, v6
	v_mov_b32_e32 v7, v25
	v_cvt_pk_bf16_f32 v2, v9, v11
	v_cvt_pk_bf16_f32 v3, v13, v15
	v_cvt_pk_bf16_f32 v4, v17, v19
	v_cvt_pk_bf16_f32 v5, v21, v37
	v_lshl_add_u64 v[6:7], v[34:35], 0, v[6:7]
	global_store_dwordx4 v[6:7], v[2:5], off nt
	s_waitcnt lgkmcnt(0)

.LBB0_194:
	s_andn2_b64 vcc, exec, s[18:19]
	s_cbranch_vccnz .LBB0_19
	s_mul_i32 s18, s96, 0xba3
	s_lshr_b32 s19, s18, 31
	s_ashr_i32 s18, s18, 24
	s_add_i32 s40, s18, s19
	s_mul_i32 s18, s40, 0x1600
	s_sub_i32 s18, s96, s18
	s_sext_i32_i16 s43, s18
	s_lshr_b32 s18, s43, 3
	s_sext_i32_i16 s19, s18
	s_mulk_i32 s19, 0xba3
	s_lshr_b32 s44, s19, 31
	s_ashr_i32 s19, s19, 17
	s_add_i32 s45, s19, s44
	s_mul_i32 s19, s45, 44
	s_sub_i32 s18, s18, s19
	s_sext_i32_i16 s18, s18
	s_lshl_b32 s19, s43, 6
	s_lshl_b32 s18, s18, 8
	s_and_b32 s19, s19, 0xc0
	s_or_b32 s44, s18, s19
	s_addk_i32 s96, 0xea00
	s_add_i32 s18, s95, 0x609f
	s_cmpk_lt_u32 s18, 0xc13f
	s_cselect_b64 s[18:19], -1, 0
	s_cmp_gt_u32 s96, 0xffffd400
	s_cselect_b64 s[46:47], -1, 0
	s_and_b64 s[18:19], s[18:19], s[46:47]
	s_lshl_b32 s46, s42, 1
	s_add_i32 s40, s46, s40
	s_mul_i32 s47, s40, 0x5800000
	s_mul_hi_i32 s46, s40, 0x5800000
	s_add_u32 s47, s2, s47
	s_addc_u32 s50, s3, s46
	s_lshl_b32 s43, s43, 4
	s_lshl_b32 s45, s45, 7
	s_and_b32 s43, s43, 64
	s_or_b32 s46, s45, s43
	s_ashr_i32 s45, s44, 31
	s_lshl_b64 s[48:49], s[44:45], 2
	v_or_b32_e32 v31, s46, v1
	s_add_u32 s48, s47, s48
	s_addc_u32 s49, s50, s49
	v_mov_b32_e32 v33, v25
	v_mul_i32_i24_e32 v2, 0x2c00, v31
	v_mad_i32_i24 v4, v31, s94, v89
	s_waitcnt vmcnt(9)
	v_mad_i32_i24 v10, v31, s94, v90
	v_mad_i32_i24 v12, v31, s94, v91
	v_mad_i32_i24 v18, v31, s94, v92
	v_mad_i32_i24 v20, v31, s94, v93
	s_waitcnt lgkmcnt(3)
	v_mad_i32_i24 v38, v31, s94, v94
	s_waitcnt lgkmcnt(2)
	v_mad_i32_i24 v40, v31, s94, v95
	s_waitcnt lgkmcnt(0)
	v_mad_i32_i24 v46, v31, s94, v96
	v_mad_i32_i24 v48, v31, s94, v97
	v_mad_i32_i24 v110, v31, s94, v98
	v_mad_i32_i24 v112, v31, s94, v99
	v_mad_i32_i24 v118, v31, s94, v100
	v_mad_i32_i24 v120, v31, s94, v101
	v_lshl_add_u64 v[130:131], s[48:49], 0, v[32:33]
	v_ashrrev_i32_e32 v3, 31, v2
	v_ashrrev_i32_e32 v5, 31, v4
	v_ashrrev_i32_e32 v11, 31, v10
	v_ashrrev_i32_e32 v13, 31, v12
	v_ashrrev_i32_e32 v19, 31, v18
	v_ashrrev_i32_e32 v21, 31, v20
	v_ashrrev_i32_e32 v39, 31, v38
	v_ashrrev_i32_e32 v41, 31, v40
	v_ashrrev_i32_e32 v47, 31, v46
	v_ashrrev_i32_e32 v49, 31, v48
	v_ashrrev_i32_e32 v111, 31, v110
	v_ashrrev_i32_e32 v113, 31, v112
	v_ashrrev_i32_e32 v119, 31, v118
	v_ashrrev_i32_e32 v121, 31, v120
	v_lshl_add_u64 v[2:3], v[2:3], 2, v[130:131]
	s_waitcnt vmcnt(8)
	v_lshl_add_u64 v[6:7], v[4:5], 2, v[130:131]
	v_lshl_add_u64 v[10:11], v[10:11], 2, v[130:131]
	v_lshl_add_u64 v[14:15], v[12:13], 2, v[130:131]
	v_lshl_add_u64 v[18:19], v[18:19], 2, v[130:131]
	v_lshl_add_u64 v[34:35], v[20:21], 2, v[130:131]
	v_lshl_add_u64 v[38:39], v[38:39], 2, v[130:131]
	v_lshl_add_u64 v[42:43], v[40:41], 2, v[130:131]
	v_lshl_add_u64 v[46:47], v[46:47], 2, v[130:131]
	v_lshl_add_u64 v[106:107], v[48:49], 2, v[130:131]
	v_lshl_add_u64 v[110:111], v[110:111], 2, v[130:131]
	v_lshl_add_u64 v[114:115], v[112:113], 2, v[130:131]
	v_lshl_add_u64 v[118:119], v[118:119], 2, v[130:131]
	v_lshl_add_u64 v[122:123], v[120:121], 2, v[130:131]
	global_load_dwordx4 v[2:5], v[2:3], off nt
	s_nop 0
	global_load_dwordx4 v[6:9], v[6:7], off nt
	s_nop 0
	global_load_dwordx4 v[10:13], v[10:11], off nt
	s_nop 0
	global_load_dwordx4 v[14:17], v[14:15], off nt
	s_nop 0
	global_load_dwordx4 v[18:21], v[18:19], off nt
	s_nop 0
	global_load_dwordx4 v[34:37], v[34:35], off nt
	s_nop 0
	global_load_dwordx4 v[38:41], v[38:39], off nt
	s_nop 0
	global_load_dwordx4 v[42:45], v[42:43], off nt
	s_nop 0
	global_load_dwordx4 v[46:49], v[46:47], off nt
	s_nop 0
	global_load_dwordx4 v[106:109], v[106:107], off nt
	s_nop 0
	global_load_dwordx4 v[110:113], v[110:111], off nt
	s_nop 0
	global_load_dwordx4 v[114:117], v[114:115], off nt
	s_nop 0
	global_load_dwordx4 v[118:121], v[118:119], off nt
	s_nop 0
	global_load_dwordx4 v[122:125], v[122:123], off nt
	v_mad_i32_i24 v126, v31, s94, v102
	v_ashrrev_i32_e32 v127, 31, v126
	v_lshl_add_u64 v[126:127], v[126:127], 2, v[130:131]
	v_mad_i32_i24 v132, v31, s94, v103
	global_load_dwordx4 v[126:129], v[126:127], off nt
	v_ashrrev_i32_e32 v133, 31, v132
	v_lshl_add_u64 v[130:131], v[132:133], 2, v[130:131]
	global_load_dwordx4 v[130:133], v[130:131], off nt
	s_or_b64 s[18:19], s[18:19], s[36:37]
	s_and_b64 vcc, exec, s[18:19]
	s_waitcnt vmcnt(15)
	ds_write2_b32 v23, v2, v3 offset1:1
	ds_write2_b32 v23, v4, v5 offset0:2 offset1:3
	s_waitcnt vmcnt(14)
	ds_write2_b32 v58, v6, v7 offset1:1
	ds_write2_b32 v59, v8, v9 offset1:1
	s_waitcnt vmcnt(13)
	ds_write2_b32 v60, v10, v11 offset1:1
	ds_write2_b32 v61, v12, v13 offset1:1
	s_waitcnt vmcnt(12)
	ds_write2_b32 v62, v14, v15 offset1:1
	ds_write2_b32 v63, v16, v17 offset1:1
	s_waitcnt vmcnt(11)
	ds_write2_b32 v64, v18, v19 offset1:1
	ds_write2_b32 v65, v20, v21 offset1:1
	s_waitcnt vmcnt(10)
	ds_write2_b32 v66, v34, v35 offset1:1
	ds_write2_b32 v67, v36, v37 offset1:1
	s_waitcnt vmcnt(9)
	ds_write2_b32 v68, v38, v39 offset1:1
	ds_write2_b32 v69, v40, v41 offset1:1
	s_waitcnt vmcnt(8)
	ds_write2_b32 v70, v42, v43 offset1:1
	ds_write2_b32 v71, v44, v45 offset1:1
	s_waitcnt vmcnt(7)
	ds_write2_b32 v72, v46, v47 offset1:1
	ds_write2_b32 v73, v48, v49 offset1:1
	s_waitcnt vmcnt(6)
	ds_write2_b32 v74, v106, v107 offset1:1
	ds_write2_b32 v75, v108, v109 offset1:1
	s_waitcnt vmcnt(5)
	ds_write2_b32 v76, v110, v111 offset1:1
	ds_write2_b32 v77, v112, v113 offset1:1
	s_waitcnt vmcnt(4)
	ds_write2_b32 v78, v114, v115 offset1:1
	ds_write2_b32 v79, v116, v117 offset1:1
	s_waitcnt vmcnt(3)
	ds_write2_b32 v80, v118, v119 offset1:1
	ds_write2_b32 v81, v120, v121 offset1:1
	s_waitcnt vmcnt(2)
	ds_write2_b32 v82, v122, v123 offset1:1
	ds_write2_b32 v83, v124, v125 offset1:1
	s_waitcnt vmcnt(1)
	ds_write2_b32 v84, v126, v127 offset1:1
	ds_write2_b32 v85, v128, v129 offset1:1
	s_waitcnt vmcnt(0)
	ds_write2_b32 v86, v130, v131 offset1:1
	ds_write2_b32 v87, v132, v133 offset1:1
	s_waitcnt lgkmcnt(0)
	s_cbranch_vccnz .LBB0_197
	s_cmpk_lt_u32 s96, 0x1600
	s_mul_i32 s42, s42, 3
	s_cselect_b32 s43, 1, -1
	s_add_i32 s42, s43, s42
	s_ashr_i32 s43, s42, 31
	s_lshl_b64 s[42:43], s[42:43], 13
	s_add_u32 s48, s30, s42
	s_addc_u32 s49, s31, s43
	v_or_b32_e32 v2, s46, v26
	s_add_u32 s42, s62, s42
	v_ashrrev_i32_e32 v3, 31, v2
	s_addc_u32 s43, s63, s43
	v_lshlrev_b64 v[10:11], 2, v[2:3]
	v_lshl_add_u64 v[2:3], s[42:43], 0, v[10:11]
	global_load_dwordx4 v[6:9], v[2:3], off nt
	s_nop 0
	global_load_dwordx4 v[2:5], v[2:3], off offset:16 nt
	v_lshl_add_u64 v[14:15], s[48:49], 0, v[10:11]
	global_load_dwordx4 v[10:13], v[14:15], off offset:16 nt
	s_nop 0
	global_load_dwordx4 v[14:17], v[14:15], off nt
	s_waitcnt vmcnt(3)
	v_mov_b32_e32 v34, v9
	s_waitcnt vmcnt(2)
	v_mov_b32_e32 v35, v2
	v_mov_b32_e32 v36, v7
	v_mov_b32_e32 v37, v8
	v_mov_b32_e32 v2, v3
	v_mov_b32_e32 v3, v4

.LBB0_239:
	global_load_dwordx4 v[32:35], v2, s[10:11]
	global_load_dwordx4 v[36:39], v2, s[10:11] offset:1024
	global_load_dwordx4 v[40:43], v2, s[10:11] offset:2048
	global_load_dwordx4 v[44:47], v2, s[10:11] offset:3072
	s_lshl_b64 s[12:13], s[12:13], 12
	v_lshl_add_u64 v[10:11], v[4:5], 0, s[12:13]
	v_lshl_add_u64 v[12:13], s[10:11], 0, v[2:3]
	v_add_co_u32_e32 v12, vcc, s14, v12
	s_add_u32 s24, s24, s26
	s_nop 0
	v_addc_co_u32_e32 v13, vcc, 0, v13, vcc
	s_addc_u32 s25, s25, s27
	s_add_u32 s6, s6, s8
	s_addc_u32 s7, s7, s9
	global_load_dwordx4 v[48:51], v[12:13], off
	global_load_dwordx4 v[52:55], v[12:13], off offset:1024
	global_load_dwordx4 v[56:59], v[12:13], off offset:2048
	global_load_dwordx4 v[60:63], v[12:13], off offset:3072
	s_cmpk_lt_i32 s24, 0x2400
	s_waitcnt vmcnt(7)
	v_cvt_pk_bf16_f32 v32, v32, v33
	v_cvt_pk_bf16_f32 v33, v34, v35
	global_store_dwordx2 v[10:11], v[32:33], off
	s_waitcnt vmcnt(7)
	v_cvt_pk_bf16_f32 v36, v36, v37
	v_cvt_pk_bf16_f32 v37, v38, v39
	global_store_dwordx2 v[10:11], v[36:37], off offset:512
	s_waitcnt vmcnt(7)
	v_cvt_pk_bf16_f32 v40, v40, v41
	v_cvt_pk_bf16_f32 v41, v42, v43
	global_store_dwordx2 v[10:11], v[40:41], off offset:1024
	s_waitcnt vmcnt(7)
	v_cvt_pk_bf16_f32 v44, v44, v45
	v_cvt_pk_bf16_f32 v45, v46, v47
	global_store_dwordx2 v[10:11], v[44:45], off offset:1536
	s_waitcnt vmcnt(7)
	v_cvt_pk_bf16_f32 v48, v48, v49
	v_cvt_pk_bf16_f32 v49, v50, v51
	global_store_dwordx2 v[10:11], v[48:49], off offset:2048
	s_waitcnt vmcnt(7)
	v_cvt_pk_bf16_f32 v52, v52, v53
	v_cvt_pk_bf16_f32 v53, v54, v55
	global_store_dwordx2 v[10:11], v[52:53], off offset:2560
	s_waitcnt vmcnt(7)
	v_cvt_pk_bf16_f32 v56, v56, v57
	v_cvt_pk_bf16_f32 v57, v58, v59
	global_store_dwordx2 v[10:11], v[56:57], off offset:3072
	s_waitcnt vmcnt(7)
	v_cvt_pk_bf16_f32 v60, v60, v61
	v_cvt_pk_bf16_f32 v61, v62, v63
	global_store_dwordx2 v[10:11], v[60:61], off offset:3584
	s_cbranch_scc0 .LBB0_242
